# head-combine rewritten by hand: lam once per group, DPP row sums, double-buffered loads, cvt_pk; units unchanged from v8
# speedup vs baseline: 1.1488x; 1.0009x over previous
; #define GASP __attribute__((address_space(1)))
; __global__ void __launch_bounds__(NWAVES * 64, 2) fwd_kernel(Args args) {
;     ...
;                         asm volatile("s_waitcnt vmcnt(0)" ::: "memory");
;                         int ln = tidp & 63; asm volatile("" : "+v"(ln));
;                         unsigned char* w2 = ws; asm volatile("" : "+s"(w2));
;                         const float lambda_init = 0.8f - 0.6f * expf(-0.3f * (float)l);
;                         const float* lq1 = (const float*)ldp(L, 18); const float* lk1 = (const float*)ldp(L, 19); const float* lq2 = (const float*)ldp(L, 20); const float* lk2 = (const float*)ldp(L, 21);
;                         const float d1 = wave_sum(lq1[l * 64 + ln] * lk1[l * 64 + ln], ln), d2 = wave_sum(lq2[l * 64 + ln] * lk2[l * 64 + ln], ln);
;                         const float lam = expf(d1) - expf(d2) + lambda_init;
;                         const int c8 = (ln & 15) * 8, sub = ln >> 4;
;                         const float* sg = (const float*)ldp(L, 22) + (size_t)l * 128 + c8;
;                         const f32x4 sg0 = *(const GASP f32x4*)sg * (1.f - lambda_init), sg1 = *(const GASP f32x4*)(sg + 4) * (1.f - lambda_init);
;                         const size_t r0 = (size_t)b * SEQ + qb * 256 + wave * 32 + sub;
;                         const bf16* O1 = (const bf16*)(w2 + WS_H); const bf16* O2 = O1 + (size_t)NTOK * 1024; const bf16* ZA = (const bf16*)(w2 + WS_ZA); bf16* YCAT = (bf16*)(w2 + WS_A2);
;                         v4u pp[8], qq[8], zz[8];
; #pragma unroll
;                         for (int it = 0; it < 8; ++it) { const size_t off = (r0 + it * 4) * 1024 + h * 128 + c8;
;                             pp[it] = *(const GASP v4u*)(O1 + off); qq[it] = *(const GASP v4u*)(O2 + off);
;                             zz[it] = *(const GASP v4u*)(ZA + off); }
.Lat_unit_done:
	s_add_i32 s73, s73, 1
	s_cmp_lt_u32 s73, 4
	s_cbranch_scc1 .Lat_qi_loop
	s_add_i32 s72, s72, 1
	s_cmp_lt_u32 s72, 2
	s_cbranch_scc1 .Lat_mp_loop
	s_waitcnt vmcnt(0)
	v_and_b32_e32 v253, 15, v239
	v_lshrrev_b32_e32 v249, 4, v239
	v_add_u32_e32 v249, s46, v249
	v_lshlrev_b32_e32 v250, 4, v253
	v_add_u32_e32 v251, 0, v249
	v_lshl_or_b32 v200, v251, 11, v250
	v_lshl_or_b32 v209, v251, 12, v250
	v_add_u32_e32 v251, 4, v249
	v_lshl_or_b32 v201, v251, 11, v250
	v_lshl_or_b32 v210, v251, 12, v250
	v_add_u32_e32 v251, 8, v249
	v_lshl_or_b32 v202, v251, 11, v250
	v_lshl_or_b32 v211, v251, 12, v250
	v_add_u32_e32 v251, 12, v249
	v_lshl_or_b32 v203, v251, 11, v250
	v_lshl_or_b32 v214, v251, 12, v250
	v_add_u32_e32 v251, 16, v249
	v_lshl_or_b32 v204, v251, 11, v250
	v_lshl_or_b32 v215, v251, 12, v250
	v_add_u32_e32 v251, 20, v249
	v_lshl_or_b32 v206, v251, 11, v250
	v_lshl_or_b32 v216, v251, 12, v250
	v_add_u32_e32 v251, 24, v249
	v_lshl_or_b32 v207, v251, 11, v250
	v_lshl_or_b32 v217, v251, 12, v250
	v_add_u32_e32 v251, 28, v249
	v_lshl_or_b32 v208, v251, 11, v250
	v_lshl_or_b32 v219, v251, 12, v250
	s_lshl_b32 s21, s75, 23
	s_lshl_b32 s32, s59, 19
	s_add_u32 s21, s21, s32
	s_lshl_b32 s32, s61, 1
	s_add_u32 s21, s21, s32
	s_add_u32 s21, s21, 0xda00000
	s_add_u32 s0, s8, s21
	s_addc_u32 s1, s9, 0
	s_add_u32 s4, s0, 0x4000000
	s_addc_u32 s5, s1, 0
	s_add_u32 s6, s0, 0x24000000
	s_addc_u32 s7, s1, 0
	global_load_dwordx4 v[0:3], v200, s[0:1]
	global_load_dwordx4 v[32:35], v200, s[4:5]
	global_load_dwordx4 v[4:7], v201, s[0:1]
	global_load_dwordx4 v[36:39], v201, s[4:5]
	global_load_dwordx4 v[8:11], v202, s[0:1]
	global_load_dwordx4 v[40:43], v202, s[4:5]
	global_load_dwordx4 v[12:15], v203, s[0:1]
	global_load_dwordx4 v[44:47], v203, s[4:5]
	global_load_dwordx4 v[16:19], v204, s[0:1]
	global_load_dwordx4 v[48:51], v204, s[4:5]
	global_load_dwordx4 v[20:23], v206, s[0:1]
	global_load_dwordx4 v[52:55], v206, s[4:5]
	global_load_dwordx4 v[24:27], v207, s[0:1]
	global_load_dwordx4 v[56:59], v207, s[4:5]
	global_load_dwordx4 v[28:31], v208, s[0:1]
	global_load_dwordx4 v[60:63], v208, s[4:5]
	global_load_dwordx4 v[64:67], v200, s[6:7]
	global_load_dwordx4 v[68:71], v201, s[6:7]
	global_load_dwordx4 v[72:75], v202, s[6:7]
	global_load_dwordx4 v[76:79], v203, s[6:7]
	global_load_dwordx4 v[80:83], v204, s[6:7]
	global_load_dwordx4 v[84:87], v206, s[6:7]
	global_load_dwordx4 v[88:91], v207, s[6:7]
	global_load_dwordx4 v[92:95], v208, s[6:7]
	v_readlane_b32 s21, v255, 51
	v_mov_b32_e32 v243, 0x20090
	ds_read_b128 v[112:115], v243
	ds_read_b128 v[116:119], v243 offset:16
	ds_read_b64 v[120:121], v243 offset:32
	s_lshl_b32 s32, s21, 6
	v_add_u32_e32 v244, s32, v239
	v_lshlrev_b32_e32 v244, 2, v244
	s_waitcnt lgkmcnt(0)
	v_readfirstlane_b32 s0, v112
	v_readfirstlane_b32 s1, v113
	v_readfirstlane_b32 s4, v114
	v_readfirstlane_b32 s5, v115
	v_readfirstlane_b32 s6, v116
	v_readfirstlane_b32 s7, v117
	v_readfirstlane_b32 s28, v118
	v_readfirstlane_b32 s29, v119
	v_readfirstlane_b32 s54, v120
	v_readfirstlane_b32 s55, v121
	s_lshl_b32 s32, s21, 9
	s_add_u32 s54, s54, s32
	s_addc_u32 s55, s55, 0
	v_lshlrev_b32_e32 v249, 5, v253
	s_nop 3
	global_load_dword v122, v244, s[0:1]
	global_load_dword v123, v244, s[4:5]
	global_load_dword v124, v244, s[6:7]
	global_load_dword v125, v244, s[28:29]
	global_load_dwordx4 v[192:195], v249, s[54:55]
	global_load_dwordx4 v[196:199], v249, s[54:55] offset:16
	v_lshlrev_b32_e32 v252, 2, v239
	s_waitcnt vmcnt(0)
	v_mul_f32_e32 v126, v122, v123
	v_mul_f32_e32 v127, v124, v125
	v_xor_b32_e32 v243, 4, v252
	ds_bpermute_b32 v128, v243, v126
	ds_bpermute_b32 v129, v243, v127
	s_waitcnt lgkmcnt(0)
	v_add_f32_e32 v126, v126, v128
	v_add_f32_e32 v127, v127, v129
	v_xor_b32_e32 v243, 8, v252
	ds_bpermute_b32 v128, v243, v126
	ds_bpermute_b32 v129, v243, v127
	s_waitcnt lgkmcnt(0)
	v_add_f32_e32 v126, v126, v128
	v_add_f32_e32 v127, v127, v129
	v_xor_b32_e32 v243, 16, v252
	ds_bpermute_b32 v128, v243, v126
	ds_bpermute_b32 v129, v243, v127
	s_waitcnt lgkmcnt(0)
	v_add_f32_e32 v126, v126, v128
	v_add_f32_e32 v127, v127, v129
	v_xor_b32_e32 v243, 32, v252
	ds_bpermute_b32 v128, v243, v126
	ds_bpermute_b32 v129, v243, v127
	s_waitcnt lgkmcnt(0)
	v_add_f32_e32 v126, v126, v128
	v_add_f32_e32 v127, v127, v129
	v_xor_b32_e32 v243, 64, v252
	ds_bpermute_b32 v128, v243, v126
	ds_bpermute_b32 v129, v243, v127
	s_waitcnt lgkmcnt(0)
	v_add_f32_e32 v126, v126, v128
	v_add_f32_e32 v127, v127, v129
	v_xor_b32_e32 v243, 128, v252
	ds_bpermute_b32 v128, v243, v126
	ds_bpermute_b32 v129, v243, v127
	s_waitcnt lgkmcnt(0)
; #define GASP __attribute__((address_space(1)))
; __device__ __forceinline__ float bflo(unsigned w) { return __uint_as_float(w << 16); }
; __device__ __forceinline__ float bfhi(unsigned w) { return __uint_as_float(w & 0xffff0000u); }
; __global__ void __launch_bounds__(NWAVES * 64, 2) fwd_kernel(Args args) {
;     ...
;                         const float d1 = wave_sum(lq1[l * 64 + ln] * lk1[l * 64 + ln], ln), d2 = wave_sum(lq2[l * 64 + ln] * lk2[l * 64 + ln], ln);
;                         const float lam = expf(d1) - expf(d2) + lambda_init;
;                         const int c8 = (ln & 15) * 8, sub = ln >> 4;
;                         const float* sg = (const float*)ldp(L, 22) + (size_t)l * 128 + c8;
;                         const f32x4 sg0 = *(const GASP f32x4*)sg * (1.f - lambda_init), sg1 = *(const GASP f32x4*)(sg + 4) * (1.f - lambda_init);
;                         const size_t r0 = (size_t)b * SEQ + qb * 256 + wave * 32 + sub;
;                         const bf16* O1 = (const bf16*)(w2 + WS_H); const bf16* O2 = O1 + (size_t)NTOK * 1024; const bf16* ZA = (const bf16*)(w2 + WS_ZA); bf16* YCAT = (bf16*)(w2 + WS_A2);
;                         v4u pp[8], qq[8], zz[8];
; #pragma unroll
;                         for (int it = 0; it < 8; ++it) { const size_t off = (r0 + it * 4) * 1024 + h * 128 + c8;
;                             pp[it] = *(const GASP v4u*)(O1 + off); qq[it] = *(const GASP v4u*)(O2 + off);
;                             zz[it] = *(const GASP v4u*)(ZA + off); }
; #pragma unroll
;                         for (int it = 0; it < 8; ++it) { const size_t row = r0 + it * 4; const v4u p = pp[it], q = qq[it], z = zz[it];
;                             float d[8]; float ss = 0.f;
; #pragma unroll
;                             for (int e = 0; e < 4; ++e) { d[2 * e] = bflo(p[e]) - lam * bflo(q[e]); d[2 * e + 1] = bfhi(p[e]) - lam * bfhi(q[e]); ss += d[2 * e] * d[2 * e] + d[2 * e + 1] * d[2 * e + 1]; }
	v_add_f32_e32 v126, v126, v128
	v_add_f32_e32 v127, v127, v129
	v_mul_f32_e32 v130, 0x3fb8aa3b, v126
	v_fma_f32 v132, v126, s91, -v130
	v_rndne_f32_e32 v133, v130
	v_fmac_f32_e32 v132, 0x32a5705f, v126
	v_sub_f32_e32 v130, v130, v133
	v_add_f32_e32 v130, v130, v132
	v_exp_f32_e32 v130, v130
	v_cvt_i32_f32_e32 v132, v133
	v_cmp_ngt_f32_e32 vcc, s40, v126
	v_ldexp_f32 v130, v130, v132
	s_nop 0
	v_cndmask_b32_e32 v130, 0, v130, vcc
	v_cmp_nlt_f32_e32 vcc, s41, v126
	s_nop 1
	v_cndmask_b32_e32 v130, v236, v130, vcc
	v_mul_f32_e32 v131, 0x3fb8aa3b, v127
	v_fma_f32 v132, v127, s91, -v131
	v_rndne_f32_e32 v133, v131
	v_fmac_f32_e32 v132, 0x32a5705f, v127
	v_sub_f32_e32 v131, v131, v133
	v_add_f32_e32 v131, v131, v132
	v_exp_f32_e32 v131, v131
	v_cvt_i32_f32_e32 v132, v133
	v_cmp_ngt_f32_e32 vcc, s40, v127
	v_ldexp_f32 v131, v131, v132
	s_nop 0
	v_cndmask_b32_e32 v131, 0, v131, vcc
	v_cmp_nlt_f32_e32 vcc, s41, v127
	s_nop 1
	v_cndmask_b32_e32 v131, v236, v131, vcc
	v_sub_f32_e32 v130, v130, v131
	v_add_f32_e32 v130, v130, v240
	v_mul_f32_e32 v192, v192, v218
	v_mul_f32_e32 v193, v193, v218
	v_mul_f32_e32 v194, v194, v218
	v_mul_f32_e32 v195, v195, v218
	v_mul_f32_e32 v196, v196, v218
	v_mul_f32_e32 v197, v197, v218
	v_mul_f32_e32 v198, v198, v218
	v_mul_f32_e32 v199, v199, v218
	v_readfirstlane_b32 s26, v130
	s_lshl_b32 s21, s75, 23
	s_lshl_b32 s32, s58, 19
	s_add_u32 s21, s21, s32
	s_lshl_b32 s32, s61, 1
	s_add_u32 s21, s21, s32
	s_add_u32 s21, s21, 0xda00000
	s_add_u32 s0, s8, s21
	s_addc_u32 s1, s9, 0
	s_add_u32 s4, s0, 0x4000000
	s_addc_u32 s5, s1, 0
	s_add_u32 s6, s0, 0x24000000
	s_addc_u32 s7, s1, 0
	global_load_dwordx4 v[96:99], v200, s[0:1]
	global_load_dwordx4 v[128:131], v200, s[4:5]
	global_load_dwordx4 v[100:103], v201, s[0:1]
	global_load_dwordx4 v[132:135], v201, s[4:5]
	global_load_dwordx4 v[104:107], v202, s[0:1]
	global_load_dwordx4 v[136:139], v202, s[4:5]
	global_load_dwordx4 v[108:111], v203, s[0:1]
	global_load_dwordx4 v[140:143], v203, s[4:5]
	global_load_dwordx4 v[112:115], v204, s[0:1]
	global_load_dwordx4 v[144:147], v204, s[4:5]
	global_load_dwordx4 v[116:119], v206, s[0:1]
	global_load_dwordx4 v[148:151], v206, s[4:5]
	global_load_dwordx4 v[120:123], v207, s[0:1]
	global_load_dwordx4 v[152:155], v207, s[4:5]
	global_load_dwordx4 v[124:127], v208, s[0:1]
	global_load_dwordx4 v[156:159], v208, s[4:5]
	global_load_dwordx4 v[160:163], v200, s[6:7]
	global_load_dwordx4 v[164:167], v201, s[6:7]
	global_load_dwordx4 v[168:171], v202, s[6:7]
	global_load_dwordx4 v[172:175], v203, s[6:7]
	global_load_dwordx4 v[176:179], v204, s[6:7]
	global_load_dwordx4 v[180:183], v206, s[6:7]
	global_load_dwordx4 v[184:187], v207, s[6:7]
	global_load_dwordx4 v[188:191], v208, s[6:7]
	s_lshl_b32 s21, s75, 24
	s_lshl_b32 s32, s59, 20
	s_add_u32 s21, s21, s32
	s_lshl_b32 s32, s61, 1
	s_add_u32 s21, s21, s32
	s_add_u32 s21, s21, 0x15a00800
	s_add_u32 s28, s8, s21
	s_addc_u32 s29, s9, 0
	s_waitcnt vmcnt(24)
	v_lshlrev_b32_e32 v249, 16, v32
	v_and_b32_e32 v250, s79, v32
	v_lshlrev_b32_e32 v251, 16, v0
	v_and_b32_e32 v252, s79, v0
	v_fma_f32 v0, -s26, v249, v251
	v_fma_f32 v32, -s26, v250, v252
	v_lshlrev_b32_e32 v249, 16, v33
	v_and_b32_e32 v250, s79, v33
	v_lshlrev_b32_e32 v251, 16, v1
	v_and_b32_e32 v252, s79, v1
	v_mul_f32_e32 v241, v0, v0
	v_mul_f32_e32 v222, v32, v32
	v_fma_f32 v1, -s26, v249, v251
	v_fma_f32 v33, -s26, v250, v252
	v_lshlrev_b32_e32 v249, 16, v34
	v_and_b32_e32 v250, s79, v34
	v_lshlrev_b32_e32 v251, 16, v2
	v_and_b32_e32 v252, s79, v2
	v_fmac_f32_e32 v241, v1, v1
	v_fmac_f32_e32 v222, v33, v33
	v_fma_f32 v2, -s26, v249, v251
	v_fma_f32 v34, -s26, v250, v252
	v_lshlrev_b32_e32 v249, 16, v35
	v_and_b32_e32 v250, s79, v35
	v_lshlrev_b32_e32 v251, 16, v3
	v_and_b32_e32 v252, s79, v3
	v_fmac_f32_e32 v241, v2, v2
	v_fmac_f32_e32 v222, v34, v34
	v_fma_f32 v3, -s26, v249, v251
	v_fma_f32 v35, -s26, v250, v252
	s_nop 0
	v_fmac_f32_e32 v241, v3, v3
	v_fmac_f32_e32 v222, v35, v35
	v_lshlrev_b32_e32 v249, 16, v36
	v_and_b32_e32 v250, s79, v36
	v_lshlrev_b32_e32 v251, 16, v4
	v_and_b32_e32 v252, s79, v4
	v_fma_f32 v4, -s26, v249, v251
	v_fma_f32 v36, -s26, v250, v252
	v_lshlrev_b32_e32 v249, 16, v37
	v_and_b32_e32 v250, s79, v37
	v_lshlrev_b32_e32 v251, 16, v5
	v_and_b32_e32 v252, s79, v5
	v_mul_f32_e32 v242, v4, v4
	v_mul_f32_e32 v223, v36, v36
	v_fma_f32 v5, -s26, v249, v251
	v_fma_f32 v37, -s26, v250, v252
	v_lshlrev_b32_e32 v249, 16, v38
	v_and_b32_e32 v250, s79, v38
	v_lshlrev_b32_e32 v251, 16, v6
	v_and_b32_e32 v252, s79, v6
	v_fmac_f32_e32 v242, v5, v5
	v_fmac_f32_e32 v223, v37, v37
	v_fma_f32 v6, -s26, v249, v251
	v_fma_f32 v38, -s26, v250, v252
	v_lshlrev_b32_e32 v249, 16, v39
	v_and_b32_e32 v250, s79, v39
	v_lshlrev_b32_e32 v251, 16, v7
	v_and_b32_e32 v252, s79, v7
	v_fmac_f32_e32 v242, v6, v6
	v_fmac_f32_e32 v223, v38, v38
	v_fma_f32 v7, -s26, v249, v251
	v_fma_f32 v39, -s26, v250, v252
	s_nop 0
	v_fmac_f32_e32 v242, v7, v7
	v_fmac_f32_e32 v223, v39, v39
	v_lshlrev_b32_e32 v249, 16, v40
	v_and_b32_e32 v250, s79, v40
	v_lshlrev_b32_e32 v251, 16, v8
	v_and_b32_e32 v252, s79, v8
	v_fma_f32 v8, -s26, v249, v251
	v_fma_f32 v40, -s26, v250, v252
	v_lshlrev_b32_e32 v249, 16, v41
	v_and_b32_e32 v250, s79, v41
	v_lshlrev_b32_e32 v251, 16, v9
	v_and_b32_e32 v252, s79, v9
	v_mul_f32_e32 v243, v8, v8
	v_mul_f32_e32 v224, v40, v40
	v_fma_f32 v9, -s26, v249, v251
	v_fma_f32 v41, -s26, v250, v252
	v_lshlrev_b32_e32 v249, 16, v42
	v_and_b32_e32 v250, s79, v42
	v_lshlrev_b32_e32 v251, 16, v10
	v_and_b32_e32 v252, s79, v10
	v_fmac_f32_e32 v243, v9, v9
	v_fmac_f32_e32 v224, v41, v41
	v_fma_f32 v10, -s26, v249, v251
	v_fma_f32 v42, -s26, v250, v252
; __device__ __forceinline__ float bflo(unsigned w) { return __uint_as_float(w << 16); }
; __device__ __forceinline__ float bfhi(unsigned w) { return __uint_as_float(w & 0xffff0000u); }
; __global__ void __launch_bounds__(NWAVES * 64, 2) fwd_kernel(Args args) {
;     ...
;                         for (int it = 0; it < 8; ++it) { const size_t row = r0 + it * 4; const v4u p = pp[it], q = qq[it], z = zz[it];
;                             float d[8]; float ss = 0.f;
; #pragma unroll
;                             for (int e = 0; e < 4; ++e) { d[2 * e] = bflo(p[e]) - lam * bflo(q[e]); d[2 * e + 1] = bfhi(p[e]) - lam * bfhi(q[e]); ss += d[2 * e] * d[2 * e] + d[2 * e + 1] * d[2 * e + 1]; }
	v_lshlrev_b32_e32 v249, 16, v43
	v_and_b32_e32 v250, s79, v43
	v_lshlrev_b32_e32 v251, 16, v11
	v_and_b32_e32 v252, s79, v11
	v_fmac_f32_e32 v243, v10, v10
	v_fmac_f32_e32 v224, v42, v42
	v_fma_f32 v11, -s26, v249, v251
	v_fma_f32 v43, -s26, v250, v252
	s_nop 0
	v_fmac_f32_e32 v243, v11, v11
	v_fmac_f32_e32 v224, v43, v43
	v_lshlrev_b32_e32 v249, 16, v44
	v_and_b32_e32 v250, s79, v44
	v_lshlrev_b32_e32 v251, 16, v12
	v_and_b32_e32 v252, s79, v12
	v_fma_f32 v12, -s26, v249, v251
	v_fma_f32 v44, -s26, v250, v252
	v_lshlrev_b32_e32 v249, 16, v45
	v_and_b32_e32 v250, s79, v45
	v_lshlrev_b32_e32 v251, 16, v13
	v_and_b32_e32 v252, s79, v13
	v_mul_f32_e32 v244, v12, v12
	v_mul_f32_e32 v225, v44, v44
	v_fma_f32 v13, -s26, v249, v251
	v_fma_f32 v45, -s26, v250, v252
	v_lshlrev_b32_e32 v249, 16, v46
	v_and_b32_e32 v250, s79, v46
	v_lshlrev_b32_e32 v251, 16, v14
	v_and_b32_e32 v252, s79, v14
	v_fmac_f32_e32 v244, v13, v13
	v_fmac_f32_e32 v225, v45, v45
	v_fma_f32 v14, -s26, v249, v251
	v_fma_f32 v46, -s26, v250, v252
	v_lshlrev_b32_e32 v249, 16, v47
	v_and_b32_e32 v250, s79, v47
	v_lshlrev_b32_e32 v251, 16, v15
	v_and_b32_e32 v252, s79, v15
	v_fmac_f32_e32 v244, v14, v14
	v_fmac_f32_e32 v225, v46, v46
	v_fma_f32 v15, -s26, v249, v251
	v_fma_f32 v47, -s26, v250, v252
	s_nop 0
	v_fmac_f32_e32 v244, v15, v15
	v_fmac_f32_e32 v225, v47, v47
	v_lshlrev_b32_e32 v249, 16, v48
	v_and_b32_e32 v250, s79, v48
	v_lshlrev_b32_e32 v251, 16, v16
	v_and_b32_e32 v252, s79, v16
	v_fma_f32 v16, -s26, v249, v251
	v_fma_f32 v48, -s26, v250, v252
	v_lshlrev_b32_e32 v249, 16, v49
	v_and_b32_e32 v250, s79, v49
	v_lshlrev_b32_e32 v251, 16, v17
	v_and_b32_e32 v252, s79, v17
	v_mul_f32_e32 v245, v16, v16
	v_mul_f32_e32 v226, v48, v48
	v_fma_f32 v17, -s26, v249, v251
	v_fma_f32 v49, -s26, v250, v252
	v_lshlrev_b32_e32 v249, 16, v50
	v_and_b32_e32 v250, s79, v50
	v_lshlrev_b32_e32 v251, 16, v18
	v_and_b32_e32 v252, s79, v18
	v_fmac_f32_e32 v245, v17, v17
	v_fmac_f32_e32 v226, v49, v49
	v_fma_f32 v18, -s26, v249, v251
	v_fma_f32 v50, -s26, v250, v252
	v_lshlrev_b32_e32 v249, 16, v51
	v_and_b32_e32 v250, s79, v51
	v_lshlrev_b32_e32 v251, 16, v19
	v_and_b32_e32 v252, s79, v19
	v_fmac_f32_e32 v245, v18, v18
	v_fmac_f32_e32 v226, v50, v50
	v_fma_f32 v19, -s26, v249, v251
	v_fma_f32 v51, -s26, v250, v252
	s_nop 0
	v_fmac_f32_e32 v245, v19, v19
	v_fmac_f32_e32 v226, v51, v51
	v_lshlrev_b32_e32 v249, 16, v52
	v_and_b32_e32 v250, s79, v52
	v_lshlrev_b32_e32 v251, 16, v20
	v_and_b32_e32 v252, s79, v20
	v_fma_f32 v20, -s26, v249, v251
	v_fma_f32 v52, -s26, v250, v252
	v_lshlrev_b32_e32 v249, 16, v53
	v_and_b32_e32 v250, s79, v53
	v_lshlrev_b32_e32 v251, 16, v21
	v_and_b32_e32 v252, s79, v21
	v_mul_f32_e32 v246, v20, v20
	v_mul_f32_e32 v227, v52, v52
	v_fma_f32 v21, -s26, v249, v251
	v_fma_f32 v53, -s26, v250, v252
	v_lshlrev_b32_e32 v249, 16, v54
	v_and_b32_e32 v250, s79, v54
	v_lshlrev_b32_e32 v251, 16, v22
	v_and_b32_e32 v252, s79, v22
	v_fmac_f32_e32 v246, v21, v21
	v_fmac_f32_e32 v227, v53, v53
	v_fma_f32 v22, -s26, v249, v251
	v_fma_f32 v54, -s26, v250, v252
	v_lshlrev_b32_e32 v249, 16, v55
	v_and_b32_e32 v250, s79, v55
	v_lshlrev_b32_e32 v251, 16, v23
	v_and_b32_e32 v252, s79, v23
	v_fmac_f32_e32 v246, v22, v22
	v_fmac_f32_e32 v227, v54, v54
	v_fma_f32 v23, -s26, v249, v251
	v_fma_f32 v55, -s26, v250, v252
	s_nop 0
	v_fmac_f32_e32 v246, v23, v23
	v_fmac_f32_e32 v227, v55, v55
	v_lshlrev_b32_e32 v249, 16, v56
	v_and_b32_e32 v250, s79, v56
	v_lshlrev_b32_e32 v251, 16, v24
	v_and_b32_e32 v252, s79, v24
	v_fma_f32 v24, -s26, v249, v251
	v_fma_f32 v56, -s26, v250, v252
	v_lshlrev_b32_e32 v249, 16, v57
	v_and_b32_e32 v250, s79, v57
	v_lshlrev_b32_e32 v251, 16, v25
	v_and_b32_e32 v252, s79, v25
	v_mul_f32_e32 v247, v24, v24
	v_mul_f32_e32 v228, v56, v56
	v_fma_f32 v25, -s26, v249, v251
	v_fma_f32 v57, -s26, v250, v252
	v_lshlrev_b32_e32 v249, 16, v58
	v_and_b32_e32 v250, s79, v58
	v_lshlrev_b32_e32 v251, 16, v26
	v_and_b32_e32 v252, s79, v26
	v_fmac_f32_e32 v247, v25, v25
	v_fmac_f32_e32 v228, v57, v57
	v_fma_f32 v26, -s26, v249, v251
	v_fma_f32 v58, -s26, v250, v252
	v_lshlrev_b32_e32 v249, 16, v59
	v_and_b32_e32 v250, s79, v59
	v_lshlrev_b32_e32 v251, 16, v27
	v_and_b32_e32 v252, s79, v27
	v_fmac_f32_e32 v247, v26, v26
	v_fmac_f32_e32 v228, v58, v58
	v_fma_f32 v27, -s26, v249, v251
	v_fma_f32 v59, -s26, v250, v252
	s_nop 0
	v_fmac_f32_e32 v247, v27, v27
	v_fmac_f32_e32 v228, v59, v59
	v_lshlrev_b32_e32 v249, 16, v60
	v_and_b32_e32 v250, s79, v60
	v_lshlrev_b32_e32 v251, 16, v28
	v_and_b32_e32 v252, s79, v28
	v_fma_f32 v28, -s26, v249, v251
	v_fma_f32 v60, -s26, v250, v252
	v_lshlrev_b32_e32 v249, 16, v61
	v_and_b32_e32 v250, s79, v61
	v_lshlrev_b32_e32 v251, 16, v29
	v_and_b32_e32 v252, s79, v29
	v_mul_f32_e32 v248, v28, v28
	v_mul_f32_e32 v229, v60, v60
	v_fma_f32 v29, -s26, v249, v251
	v_fma_f32 v61, -s26, v250, v252
	v_lshlrev_b32_e32 v249, 16, v62
	v_and_b32_e32 v250, s79, v62
	v_lshlrev_b32_e32 v251, 16, v30
	v_and_b32_e32 v252, s79, v30
	v_fmac_f32_e32 v248, v29, v29
	v_fmac_f32_e32 v229, v61, v61
	v_fma_f32 v30, -s26, v249, v251
	v_fma_f32 v62, -s26, v250, v252
	v_lshlrev_b32_e32 v249, 16, v63
	v_and_b32_e32 v250, s79, v63
	v_lshlrev_b32_e32 v251, 16, v31
	v_and_b32_e32 v252, s79, v31
	v_fmac_f32_e32 v248, v30, v30
	v_fmac_f32_e32 v229, v62, v62
	v_fma_f32 v31, -s26, v249, v251
	v_fma_f32 v63, -s26, v250, v252
	s_nop 0
	v_fmac_f32_e32 v248, v31, v31
	v_fmac_f32_e32 v229, v63, v63
	v_add_f32_e32 v241, v241, v222
	v_add_f32_e32 v242, v242, v223
	v_add_f32_e32 v243, v243, v224
	v_add_f32_e32 v244, v244, v225
	v_add_f32_e32 v245, v245, v226
	v_add_f32_e32 v246, v246, v227
; #define GASP __attribute__((address_space(1)))
; __device__ __forceinline__ float lane_xor(float v, int lane, int o) { return __int_as_float(__builtin_amdgcn_ds_bpermute((lane ^ o) << 2, __float_as_int(v))); }
; __device__ __forceinline__ unsigned pk2(float lo, float hi) { return f2bf(lo) | (f2bf(hi) << 16); }
; __device__ __forceinline__ float bflo(unsigned w) { return __uint_as_float(w << 16); }
; __device__ __forceinline__ float bfhi(unsigned w) { return __uint_as_float(w & 0xffff0000u); }
; __global__ void __launch_bounds__(NWAVES * 64, 2) fwd_kernel(Args args) {
;     ...
;                             ss += lane_xor(ss, ln, 1); ss += lane_xor(ss, ln, 2); ss += lane_xor(ss, ln, 4); ss += lane_xor(ss, ln, 8);
;                             const float r = 1.0f / sqrtf(ss * (1.f / 128.f) + 1e-6f);
;                             v4u o;
;                             o[0] = pk2(d[0] * r * sg0[0] * bflo(z[0]), d[1] * r * sg0[1] * bfhi(z[0])); o[1] = pk2(d[2] * r * sg0[2] * bflo(z[1]), d[3] * r * sg0[3] * bfhi(z[1]));
;                             o[2] = pk2(d[4] * r * sg1[0] * bflo(z[2]), d[5] * r * sg1[1] * bfhi(z[2])); o[3] = pk2(d[6] * r * sg1[2] * bflo(z[3]), d[7] * r * sg1[3] * bfhi(z[3]));
;                             *(GASP v4u*)(YCAT + row * 2048 + 1024 + h * 128 + c8) = o; }
	v_add_f32_e32 v247, v247, v228
	v_add_f32_e32 v248, v248, v229
	v_add_f32_dpp v241, v241, v241 quad_perm:[1,0,3,2] row_mask:0xf bank_mask:0xf
	v_add_f32_dpp v242, v242, v242 quad_perm:[1,0,3,2] row_mask:0xf bank_mask:0xf
	v_add_f32_dpp v243, v243, v243 quad_perm:[1,0,3,2] row_mask:0xf bank_mask:0xf
	v_add_f32_dpp v244, v244, v244 quad_perm:[1,0,3,2] row_mask:0xf bank_mask:0xf
	v_add_f32_dpp v245, v245, v245 quad_perm:[1,0,3,2] row_mask:0xf bank_mask:0xf
	v_add_f32_dpp v246, v246, v246 quad_perm:[1,0,3,2] row_mask:0xf bank_mask:0xf
	v_add_f32_dpp v247, v247, v247 quad_perm:[1,0,3,2] row_mask:0xf bank_mask:0xf
	v_add_f32_dpp v248, v248, v248 quad_perm:[1,0,3,2] row_mask:0xf bank_mask:0xf
	v_add_f32_dpp v241, v241, v241 quad_perm:[2,3,0,1] row_mask:0xf bank_mask:0xf
	v_add_f32_dpp v242, v242, v242 quad_perm:[2,3,0,1] row_mask:0xf bank_mask:0xf
	v_add_f32_dpp v243, v243, v243 quad_perm:[2,3,0,1] row_mask:0xf bank_mask:0xf
	v_add_f32_dpp v244, v244, v244 quad_perm:[2,3,0,1] row_mask:0xf bank_mask:0xf
	v_add_f32_dpp v245, v245, v245 quad_perm:[2,3,0,1] row_mask:0xf bank_mask:0xf
	v_add_f32_dpp v246, v246, v246 quad_perm:[2,3,0,1] row_mask:0xf bank_mask:0xf
	v_add_f32_dpp v247, v247, v247 quad_perm:[2,3,0,1] row_mask:0xf bank_mask:0xf
	v_add_f32_dpp v248, v248, v248 quad_perm:[2,3,0,1] row_mask:0xf bank_mask:0xf
	v_add_f32_dpp v241, v241, v241 row_ror:4 row_mask:0xf bank_mask:0xf
	v_add_f32_dpp v242, v242, v242 row_ror:4 row_mask:0xf bank_mask:0xf
	v_add_f32_dpp v243, v243, v243 row_ror:4 row_mask:0xf bank_mask:0xf
	v_add_f32_dpp v244, v244, v244 row_ror:4 row_mask:0xf bank_mask:0xf
	v_add_f32_dpp v245, v245, v245 row_ror:4 row_mask:0xf bank_mask:0xf
	v_add_f32_dpp v246, v246, v246 row_ror:4 row_mask:0xf bank_mask:0xf
	v_add_f32_dpp v247, v247, v247 row_ror:4 row_mask:0xf bank_mask:0xf
	v_add_f32_dpp v248, v248, v248 row_ror:4 row_mask:0xf bank_mask:0xf
	v_add_f32_dpp v241, v241, v241 row_ror:8 row_mask:0xf bank_mask:0xf
	v_add_f32_dpp v242, v242, v242 row_ror:8 row_mask:0xf bank_mask:0xf
	v_add_f32_dpp v243, v243, v243 row_ror:8 row_mask:0xf bank_mask:0xf
	v_add_f32_dpp v244, v244, v244 row_ror:8 row_mask:0xf bank_mask:0xf
	v_add_f32_dpp v245, v245, v245 row_ror:8 row_mask:0xf bank_mask:0xf
	v_add_f32_dpp v246, v246, v246 row_ror:8 row_mask:0xf bank_mask:0xf
	v_add_f32_dpp v247, v247, v247 row_ror:8 row_mask:0xf bank_mask:0xf
	v_add_f32_dpp v248, v248, v248 row_ror:8 row_mask:0xf bank_mask:0xf
	v_fmamk_f32 v241, v241, 0x3c000000, v231
	v_fmamk_f32 v242, v242, 0x3c000000, v231
	v_fmamk_f32 v243, v243, 0x3c000000, v231
	v_fmamk_f32 v244, v244, 0x3c000000, v231
	v_fmamk_f32 v245, v245, 0x3c000000, v231
	v_fmamk_f32 v246, v246, 0x3c000000, v231
	v_fmamk_f32 v247, v247, 0x3c000000, v231
	v_fmamk_f32 v248, v248, 0x3c000000, v231
	v_rsq_f32_e32 v241, v241
	v_rsq_f32_e32 v242, v242
	v_rsq_f32_e32 v243, v243
	v_rsq_f32_e32 v244, v244
	v_rsq_f32_e32 v245, v245
	v_rsq_f32_e32 v246, v246
	v_rsq_f32_e32 v247, v247
	v_rsq_f32_e32 v248, v248
	v_lshlrev_b32_e32 v249, 16, v64
	v_and_b32_e32 v250, s79, v64
	v_mul_f32_e32 v0, v0, v241
	v_mul_f32_e32 v32, v32, v241
	v_mul_f32_e32 v0, v0, v192
	v_mul_f32_e32 v32, v32, v193
	v_mul_f32_e32 v0, v0, v249
	v_mul_f32_e32 v32, v32, v250
	v_cvt_pk_bf16_f32 v64, v0, v32
	v_lshlrev_b32_e32 v251, 16, v65
	v_and_b32_e32 v252, s79, v65
	v_mul_f32_e32 v1, v1, v241
	v_mul_f32_e32 v33, v33, v241
	v_mul_f32_e32 v1, v1, v194
	v_mul_f32_e32 v33, v33, v195
	v_mul_f32_e32 v1, v1, v251
	v_mul_f32_e32 v33, v33, v252
	v_cvt_pk_bf16_f32 v65, v1, v33
	v_lshlrev_b32_e32 v249, 16, v66
	v_and_b32_e32 v250, s79, v66
	v_mul_f32_e32 v2, v2, v241
	v_mul_f32_e32 v34, v34, v241
	v_mul_f32_e32 v2, v2, v196
	v_mul_f32_e32 v34, v34, v197
	v_mul_f32_e32 v2, v2, v249
	v_mul_f32_e32 v34, v34, v250
	v_cvt_pk_bf16_f32 v66, v2, v34
	v_lshlrev_b32_e32 v251, 16, v67
	v_and_b32_e32 v252, s79, v67
	v_mul_f32_e32 v3, v3, v241
	v_mul_f32_e32 v35, v35, v241
	v_mul_f32_e32 v3, v3, v198
	v_mul_f32_e32 v35, v35, v199
	v_mul_f32_e32 v3, v3, v251
	v_mul_f32_e32 v35, v35, v252
	v_cvt_pk_bf16_f32 v67, v3, v35
	global_store_dwordx4 v209, v[64:67], s[28:29]
	v_lshlrev_b32_e32 v249, 16, v68
	v_and_b32_e32 v250, s79, v68
	v_mul_f32_e32 v4, v4, v242
	v_mul_f32_e32 v36, v36, v242
	v_mul_f32_e32 v4, v4, v192
	v_mul_f32_e32 v36, v36, v193
	v_mul_f32_e32 v4, v4, v249
	v_mul_f32_e32 v36, v36, v250
	v_cvt_pk_bf16_f32 v68, v4, v36
	v_lshlrev_b32_e32 v251, 16, v69
	v_and_b32_e32 v252, s79, v69
	v_mul_f32_e32 v5, v5, v242
	v_mul_f32_e32 v37, v37, v242
	v_mul_f32_e32 v5, v5, v194
	v_mul_f32_e32 v37, v37, v195
	v_mul_f32_e32 v5, v5, v251
	v_mul_f32_e32 v37, v37, v252
	v_cvt_pk_bf16_f32 v69, v5, v37
	v_lshlrev_b32_e32 v249, 16, v70
	v_and_b32_e32 v250, s79, v70
	v_mul_f32_e32 v6, v6, v242
	v_mul_f32_e32 v38, v38, v242
	v_mul_f32_e32 v6, v6, v196
	v_mul_f32_e32 v38, v38, v197
	v_mul_f32_e32 v6, v6, v249
	v_mul_f32_e32 v38, v38, v250
	v_cvt_pk_bf16_f32 v70, v6, v38
	v_lshlrev_b32_e32 v251, 16, v71
	v_and_b32_e32 v252, s79, v71
	v_mul_f32_e32 v7, v7, v242
	v_mul_f32_e32 v39, v39, v242
	v_mul_f32_e32 v7, v7, v198
	v_mul_f32_e32 v39, v39, v199
	v_mul_f32_e32 v7, v7, v251
	v_mul_f32_e32 v39, v39, v252
	v_cvt_pk_bf16_f32 v71, v7, v39
	global_store_dwordx4 v210, v[68:71], s[28:29]
	v_lshlrev_b32_e32 v249, 16, v72
	v_and_b32_e32 v250, s79, v72
	v_mul_f32_e32 v8, v8, v243
	v_mul_f32_e32 v40, v40, v243
	v_mul_f32_e32 v8, v8, v192
	v_mul_f32_e32 v40, v40, v193
	v_mul_f32_e32 v8, v8, v249
	v_mul_f32_e32 v40, v40, v250
	v_cvt_pk_bf16_f32 v72, v8, v40
	v_lshlrev_b32_e32 v251, 16, v73
	v_and_b32_e32 v252, s79, v73
	v_mul_f32_e32 v9, v9, v243
	v_mul_f32_e32 v41, v41, v243
	v_mul_f32_e32 v9, v9, v194
; #define GASP __attribute__((address_space(1)))
; __device__ __forceinline__ unsigned pk2(float lo, float hi) { return f2bf(lo) | (f2bf(hi) << 16); }
; __device__ __forceinline__ float bflo(unsigned w) { return __uint_as_float(w << 16); }
; __device__ __forceinline__ float bfhi(unsigned w) { return __uint_as_float(w & 0xffff0000u); }
; __global__ void __launch_bounds__(NWAVES * 64, 2) fwd_kernel(Args args) {
;     ...
;                             v4u o;
;                             o[0] = pk2(d[0] * r * sg0[0] * bflo(z[0]), d[1] * r * sg0[1] * bfhi(z[0])); o[1] = pk2(d[2] * r * sg0[2] * bflo(z[1]), d[3] * r * sg0[3] * bfhi(z[1]));
;                             o[2] = pk2(d[4] * r * sg1[0] * bflo(z[2]), d[5] * r * sg1[1] * bfhi(z[2])); o[3] = pk2(d[6] * r * sg1[2] * bflo(z[3]), d[7] * r * sg1[3] * bfhi(z[3]));
;                             *(GASP v4u*)(YCAT + row * 2048 + 1024 + h * 128 + c8) = o; }
	v_mul_f32_e32 v41, v41, v195
	v_mul_f32_e32 v9, v9, v251
	v_mul_f32_e32 v41, v41, v252
	v_cvt_pk_bf16_f32 v73, v9, v41
	v_lshlrev_b32_e32 v249, 16, v74
	v_and_b32_e32 v250, s79, v74
	v_mul_f32_e32 v10, v10, v243
	v_mul_f32_e32 v42, v42, v243
	v_mul_f32_e32 v10, v10, v196
	v_mul_f32_e32 v42, v42, v197
	v_mul_f32_e32 v10, v10, v249
	v_mul_f32_e32 v42, v42, v250
	v_cvt_pk_bf16_f32 v74, v10, v42
	v_lshlrev_b32_e32 v251, 16, v75
	v_and_b32_e32 v252, s79, v75
	v_mul_f32_e32 v11, v11, v243
	v_mul_f32_e32 v43, v43, v243
	v_mul_f32_e32 v11, v11, v198
	v_mul_f32_e32 v43, v43, v199
	v_mul_f32_e32 v11, v11, v251
	v_mul_f32_e32 v43, v43, v252
	v_cvt_pk_bf16_f32 v75, v11, v43
	global_store_dwordx4 v211, v[72:75], s[28:29]
	v_lshlrev_b32_e32 v249, 16, v76
	v_and_b32_e32 v250, s79, v76
	v_mul_f32_e32 v12, v12, v244
	v_mul_f32_e32 v44, v44, v244
	v_mul_f32_e32 v12, v12, v192
	v_mul_f32_e32 v44, v44, v193
	v_mul_f32_e32 v12, v12, v249
	v_mul_f32_e32 v44, v44, v250
	v_cvt_pk_bf16_f32 v76, v12, v44
	v_lshlrev_b32_e32 v251, 16, v77
	v_and_b32_e32 v252, s79, v77
	v_mul_f32_e32 v13, v13, v244
	v_mul_f32_e32 v45, v45, v244
	v_mul_f32_e32 v13, v13, v194
	v_mul_f32_e32 v45, v45, v195
	v_mul_f32_e32 v13, v13, v251
	v_mul_f32_e32 v45, v45, v252
	v_cvt_pk_bf16_f32 v77, v13, v45
	v_lshlrev_b32_e32 v249, 16, v78
	v_and_b32_e32 v250, s79, v78
	v_mul_f32_e32 v14, v14, v244
	v_mul_f32_e32 v46, v46, v244
	v_mul_f32_e32 v14, v14, v196
	v_mul_f32_e32 v46, v46, v197
	v_mul_f32_e32 v14, v14, v249
	v_mul_f32_e32 v46, v46, v250
	v_cvt_pk_bf16_f32 v78, v14, v46
	v_lshlrev_b32_e32 v251, 16, v79
	v_and_b32_e32 v252, s79, v79
	v_mul_f32_e32 v15, v15, v244
	v_mul_f32_e32 v47, v47, v244
	v_mul_f32_e32 v15, v15, v198
	v_mul_f32_e32 v47, v47, v199
	v_mul_f32_e32 v15, v15, v251
	v_mul_f32_e32 v47, v47, v252
	v_cvt_pk_bf16_f32 v79, v15, v47
	global_store_dwordx4 v214, v[76:79], s[28:29]
	v_lshlrev_b32_e32 v249, 16, v80
	v_and_b32_e32 v250, s79, v80
	v_mul_f32_e32 v16, v16, v245
	v_mul_f32_e32 v48, v48, v245
	v_mul_f32_e32 v16, v16, v192
	v_mul_f32_e32 v48, v48, v193
	v_mul_f32_e32 v16, v16, v249
	v_mul_f32_e32 v48, v48, v250
	v_cvt_pk_bf16_f32 v80, v16, v48
	v_lshlrev_b32_e32 v251, 16, v81
	v_and_b32_e32 v252, s79, v81
	v_mul_f32_e32 v17, v17, v245
	v_mul_f32_e32 v49, v49, v245
	v_mul_f32_e32 v17, v17, v194
	v_mul_f32_e32 v49, v49, v195
	v_mul_f32_e32 v17, v17, v251
	v_mul_f32_e32 v49, v49, v252
	v_cvt_pk_bf16_f32 v81, v17, v49
	v_lshlrev_b32_e32 v249, 16, v82
	v_and_b32_e32 v250, s79, v82
	v_mul_f32_e32 v18, v18, v245
	v_mul_f32_e32 v50, v50, v245
	v_mul_f32_e32 v18, v18, v196
	v_mul_f32_e32 v50, v50, v197
	v_mul_f32_e32 v18, v18, v249
	v_mul_f32_e32 v50, v50, v250
	v_cvt_pk_bf16_f32 v82, v18, v50
	v_lshlrev_b32_e32 v251, 16, v83
	v_and_b32_e32 v252, s79, v83
	v_mul_f32_e32 v19, v19, v245
	v_mul_f32_e32 v51, v51, v245
	v_mul_f32_e32 v19, v19, v198
	v_mul_f32_e32 v51, v51, v199
	v_mul_f32_e32 v19, v19, v251
	v_mul_f32_e32 v51, v51, v252
	v_cvt_pk_bf16_f32 v83, v19, v51
	global_store_dwordx4 v215, v[80:83], s[28:29]
	v_lshlrev_b32_e32 v249, 16, v84
	v_and_b32_e32 v250, s79, v84
	v_mul_f32_e32 v20, v20, v246
	v_mul_f32_e32 v52, v52, v246
	v_mul_f32_e32 v20, v20, v192
	v_mul_f32_e32 v52, v52, v193
	v_mul_f32_e32 v20, v20, v249
	v_mul_f32_e32 v52, v52, v250
	v_cvt_pk_bf16_f32 v84, v20, v52
	v_lshlrev_b32_e32 v251, 16, v85
	v_and_b32_e32 v252, s79, v85
	v_mul_f32_e32 v21, v21, v246
	v_mul_f32_e32 v53, v53, v246
	v_mul_f32_e32 v21, v21, v194
	v_mul_f32_e32 v53, v53, v195
	v_mul_f32_e32 v21, v21, v251
	v_mul_f32_e32 v53, v53, v252
	v_cvt_pk_bf16_f32 v85, v21, v53
	v_lshlrev_b32_e32 v249, 16, v86
	v_and_b32_e32 v250, s79, v86
	v_mul_f32_e32 v22, v22, v246
	v_mul_f32_e32 v54, v54, v246
	v_mul_f32_e32 v22, v22, v196
	v_mul_f32_e32 v54, v54, v197
	v_mul_f32_e32 v22, v22, v249
	v_mul_f32_e32 v54, v54, v250
	v_cvt_pk_bf16_f32 v86, v22, v54
	v_lshlrev_b32_e32 v251, 16, v87
	v_and_b32_e32 v252, s79, v87
	v_mul_f32_e32 v23, v23, v246
	v_mul_f32_e32 v55, v55, v246
	v_mul_f32_e32 v23, v23, v198
	v_mul_f32_e32 v55, v55, v199
	v_mul_f32_e32 v23, v23, v251
	v_mul_f32_e32 v55, v55, v252
	v_cvt_pk_bf16_f32 v87, v23, v55
	global_store_dwordx4 v216, v[84:87], s[28:29]
	v_lshlrev_b32_e32 v249, 16, v88
	v_and_b32_e32 v250, s79, v88
	v_mul_f32_e32 v24, v24, v247
	v_mul_f32_e32 v56, v56, v247
	v_mul_f32_e32 v24, v24, v192
	v_mul_f32_e32 v56, v56, v193
	v_mul_f32_e32 v24, v24, v249
	v_mul_f32_e32 v56, v56, v250
	v_cvt_pk_bf16_f32 v88, v24, v56
	v_lshlrev_b32_e32 v251, 16, v89
	v_and_b32_e32 v252, s79, v89
	v_mul_f32_e32 v25, v25, v247
	v_mul_f32_e32 v57, v57, v247
	v_mul_f32_e32 v25, v25, v194
	v_mul_f32_e32 v57, v57, v195
	v_mul_f32_e32 v25, v25, v251
	v_mul_f32_e32 v57, v57, v252
	v_cvt_pk_bf16_f32 v89, v25, v57
	v_lshlrev_b32_e32 v249, 16, v90
	v_and_b32_e32 v250, s79, v90
	v_mul_f32_e32 v26, v26, v247
	v_mul_f32_e32 v58, v58, v247
	v_mul_f32_e32 v26, v26, v196
	v_mul_f32_e32 v58, v58, v197
	v_mul_f32_e32 v26, v26, v249
	v_mul_f32_e32 v58, v58, v250
	v_cvt_pk_bf16_f32 v90, v26, v58
	v_lshlrev_b32_e32 v251, 16, v91
	v_and_b32_e32 v252, s79, v91
	v_mul_f32_e32 v27, v27, v247
	v_mul_f32_e32 v59, v59, v247
	v_mul_f32_e32 v27, v27, v198
	v_mul_f32_e32 v59, v59, v199
	v_mul_f32_e32 v27, v27, v251
	v_mul_f32_e32 v59, v59, v252
	v_cvt_pk_bf16_f32 v91, v27, v59
	global_store_dwordx4 v217, v[88:91], s[28:29]
	v_lshlrev_b32_e32 v249, 16, v92
	v_and_b32_e32 v250, s79, v92
	v_mul_f32_e32 v28, v28, v248
	v_mul_f32_e32 v60, v60, v248
	v_mul_f32_e32 v28, v28, v192
	v_mul_f32_e32 v60, v60, v193
	v_mul_f32_e32 v28, v28, v249
	v_mul_f32_e32 v60, v60, v250
	v_cvt_pk_bf16_f32 v92, v28, v60
	v_lshlrev_b32_e32 v251, 16, v93
; #define GASP __attribute__((address_space(1)))
; __device__ __forceinline__ float lane_xor(float v, int lane, int o) { return __int_as_float(__builtin_amdgcn_ds_bpermute((lane ^ o) << 2, __float_as_int(v))); }
; __device__ __forceinline__ unsigned pk2(float lo, float hi) { return f2bf(lo) | (f2bf(hi) << 16); }
; __device__ __forceinline__ float bflo(unsigned w) { return __uint_as_float(w << 16); }
; __device__ __forceinline__ float bfhi(unsigned w) { return __uint_as_float(w & 0xffff0000u); }
; __global__ void __launch_bounds__(NWAVES * 64, 2) fwd_kernel(Args args) {
;     ...
;                         for (int it = 0; it < 8; ++it) { const size_t off = (r0 + it * 4) * 1024 + h * 128 + c8;
;                             pp[it] = *(const GASP v4u*)(O1 + off); qq[it] = *(const GASP v4u*)(O2 + off);
;                             zz[it] = *(const GASP v4u*)(ZA + off); }
; #pragma unroll
;                         for (int it = 0; it < 8; ++it) { const size_t row = r0 + it * 4; const v4u p = pp[it], q = qq[it], z = zz[it];
;                             float d[8]; float ss = 0.f;
; #pragma unroll
;                             for (int e = 0; e < 4; ++e) { d[2 * e] = bflo(p[e]) - lam * bflo(q[e]); d[2 * e + 1] = bfhi(p[e]) - lam * bfhi(q[e]); ss += d[2 * e] * d[2 * e] + d[2 * e + 1] * d[2 * e + 1]; }
;                             ss += lane_xor(ss, ln, 1); ss += lane_xor(ss, ln, 2); ss += lane_xor(ss, ln, 4); ss += lane_xor(ss, ln, 8);
;                             const float r = 1.0f / sqrtf(ss * (1.f / 128.f) + 1e-6f);
;                             v4u o;
;                             o[0] = pk2(d[0] * r * sg0[0] * bflo(z[0]), d[1] * r * sg0[1] * bfhi(z[0])); o[1] = pk2(d[2] * r * sg0[2] * bflo(z[1]), d[3] * r * sg0[3] * bfhi(z[1]));
;                             o[2] = pk2(d[4] * r * sg1[0] * bflo(z[2]), d[5] * r * sg1[1] * bfhi(z[2])); o[3] = pk2(d[6] * r * sg1[2] * bflo(z[3]), d[7] * r * sg1[3] * bfhi(z[3]));
;                             *(GASP v4u*)(YCAT + row * 2048 + 1024 + h * 128 + c8) = o; }
	v_and_b32_e32 v252, s79, v93
	v_mul_f32_e32 v29, v29, v248
	v_mul_f32_e32 v61, v61, v248
	v_mul_f32_e32 v29, v29, v194
	v_mul_f32_e32 v61, v61, v195
	v_mul_f32_e32 v29, v29, v251
	v_mul_f32_e32 v61, v61, v252
	v_cvt_pk_bf16_f32 v93, v29, v61
	v_lshlrev_b32_e32 v249, 16, v94
	v_and_b32_e32 v250, s79, v94
	v_mul_f32_e32 v30, v30, v248
	v_mul_f32_e32 v62, v62, v248
	v_mul_f32_e32 v30, v30, v196
	v_mul_f32_e32 v62, v62, v197
	v_mul_f32_e32 v30, v30, v249
	v_mul_f32_e32 v62, v62, v250
	v_cvt_pk_bf16_f32 v94, v30, v62
	v_lshlrev_b32_e32 v251, 16, v95
	v_and_b32_e32 v252, s79, v95
	v_mul_f32_e32 v31, v31, v248
	v_mul_f32_e32 v63, v63, v248
	v_mul_f32_e32 v31, v31, v198
	v_mul_f32_e32 v63, v63, v199
	v_mul_f32_e32 v31, v31, v251
	v_mul_f32_e32 v63, v63, v252
	v_cvt_pk_bf16_f32 v95, v31, v63
	global_store_dwordx4 v219, v[92:95], s[28:29]
	s_lshl_b32 s21, s75, 23
	s_lshl_b32 s32, s60, 19
	s_add_u32 s21, s21, s32
	s_lshl_b32 s32, s61, 1
	s_add_u32 s21, s21, s32
	s_add_u32 s21, s21, 0xda00000
	s_add_u32 s0, s8, s21
	s_addc_u32 s1, s9, 0
	s_add_u32 s4, s0, 0x4000000
	s_addc_u32 s5, s1, 0
	s_add_u32 s6, s0, 0x24000000
	s_addc_u32 s7, s1, 0
	global_load_dwordx4 v[0:3], v200, s[0:1]
	global_load_dwordx4 v[32:35], v200, s[4:5]
	global_load_dwordx4 v[4:7], v201, s[0:1]
	global_load_dwordx4 v[36:39], v201, s[4:5]
	global_load_dwordx4 v[8:11], v202, s[0:1]
	global_load_dwordx4 v[40:43], v202, s[4:5]
	global_load_dwordx4 v[12:15], v203, s[0:1]
	global_load_dwordx4 v[44:47], v203, s[4:5]
	global_load_dwordx4 v[16:19], v204, s[0:1]
	global_load_dwordx4 v[48:51], v204, s[4:5]
	global_load_dwordx4 v[20:23], v206, s[0:1]
	global_load_dwordx4 v[52:55], v206, s[4:5]
	global_load_dwordx4 v[24:27], v207, s[0:1]
	global_load_dwordx4 v[56:59], v207, s[4:5]
	global_load_dwordx4 v[28:31], v208, s[0:1]
	global_load_dwordx4 v[60:63], v208, s[4:5]
	global_load_dwordx4 v[64:67], v200, s[6:7]
	global_load_dwordx4 v[68:71], v201, s[6:7]
	global_load_dwordx4 v[72:75], v202, s[6:7]
	global_load_dwordx4 v[76:79], v203, s[6:7]
	global_load_dwordx4 v[80:83], v204, s[6:7]
	global_load_dwordx4 v[84:87], v206, s[6:7]
	global_load_dwordx4 v[88:91], v207, s[6:7]
	global_load_dwordx4 v[92:95], v208, s[6:7]
	s_lshl_b32 s21, s75, 24
	s_lshl_b32 s32, s58, 20
	s_add_u32 s21, s21, s32
	s_lshl_b32 s32, s61, 1
	s_add_u32 s21, s21, s32
	s_add_u32 s21, s21, 0x15a00800
	s_add_u32 s28, s8, s21
	s_addc_u32 s29, s9, 0
	s_waitcnt vmcnt(32)
	v_lshlrev_b32_e32 v249, 16, v128
	v_and_b32_e32 v250, s79, v128
	v_lshlrev_b32_e32 v251, 16, v96
	v_and_b32_e32 v252, s79, v96
	v_fma_f32 v96, -s26, v249, v251
	v_fma_f32 v128, -s26, v250, v252
	v_lshlrev_b32_e32 v249, 16, v129
	v_and_b32_e32 v250, s79, v129
	v_lshlrev_b32_e32 v251, 16, v97
	v_and_b32_e32 v252, s79, v97
	v_mul_f32_e32 v241, v96, v96
	v_mul_f32_e32 v222, v128, v128
	v_fma_f32 v97, -s26, v249, v251
	v_fma_f32 v129, -s26, v250, v252
	v_lshlrev_b32_e32 v249, 16, v130
	v_and_b32_e32 v250, s79, v130
	v_lshlrev_b32_e32 v251, 16, v98
	v_and_b32_e32 v252, s79, v98
	v_fmac_f32_e32 v241, v97, v97
	v_fmac_f32_e32 v222, v129, v129
	v_fma_f32 v98, -s26, v249, v251
	v_fma_f32 v130, -s26, v250, v252
	v_lshlrev_b32_e32 v249, 16, v131
	v_and_b32_e32 v250, s79, v131
	v_lshlrev_b32_e32 v251, 16, v99
	v_and_b32_e32 v252, s79, v99
	v_fmac_f32_e32 v241, v98, v98
	v_fmac_f32_e32 v222, v130, v130
	v_fma_f32 v99, -s26, v249, v251
	v_fma_f32 v131, -s26, v250, v252
	s_nop 0
	v_fmac_f32_e32 v241, v99, v99
	v_fmac_f32_e32 v222, v131, v131
	v_lshlrev_b32_e32 v249, 16, v132
	v_and_b32_e32 v250, s79, v132
	v_lshlrev_b32_e32 v251, 16, v100
	v_and_b32_e32 v252, s79, v100
	v_fma_f32 v100, -s26, v249, v251
	v_fma_f32 v132, -s26, v250, v252
	v_lshlrev_b32_e32 v249, 16, v133
	v_and_b32_e32 v250, s79, v133
	v_lshlrev_b32_e32 v251, 16, v101
	v_and_b32_e32 v252, s79, v101
	v_mul_f32_e32 v242, v100, v100
	v_mul_f32_e32 v223, v132, v132
	v_fma_f32 v101, -s26, v249, v251
	v_fma_f32 v133, -s26, v250, v252
	v_lshlrev_b32_e32 v249, 16, v134
	v_and_b32_e32 v250, s79, v134
	v_lshlrev_b32_e32 v251, 16, v102
	v_and_b32_e32 v252, s79, v102
	v_fmac_f32_e32 v242, v101, v101
	v_fmac_f32_e32 v223, v133, v133
	v_fma_f32 v102, -s26, v249, v251
	v_fma_f32 v134, -s26, v250, v252
	v_lshlrev_b32_e32 v249, 16, v135
	v_and_b32_e32 v250, s79, v135
	v_lshlrev_b32_e32 v251, 16, v103
	v_and_b32_e32 v252, s79, v103
	v_fmac_f32_e32 v242, v102, v102
	v_fmac_f32_e32 v223, v134, v134
	v_fma_f32 v103, -s26, v249, v251
	v_fma_f32 v135, -s26, v250, v252
	s_nop 0
	v_fmac_f32_e32 v242, v103, v103
	v_fmac_f32_e32 v223, v135, v135
	v_lshlrev_b32_e32 v249, 16, v136
	v_and_b32_e32 v250, s79, v136
	v_lshlrev_b32_e32 v251, 16, v104
	v_and_b32_e32 v252, s79, v104
	v_fma_f32 v104, -s26, v249, v251
	v_fma_f32 v136, -s26, v250, v252
	v_lshlrev_b32_e32 v249, 16, v137
	v_and_b32_e32 v250, s79, v137
	v_lshlrev_b32_e32 v251, 16, v105
	v_and_b32_e32 v252, s79, v105
	v_mul_f32_e32 v243, v104, v104
	v_mul_f32_e32 v224, v136, v136
	v_fma_f32 v105, -s26, v249, v251
	v_fma_f32 v137, -s26, v250, v252
	v_lshlrev_b32_e32 v249, 16, v138
	v_and_b32_e32 v250, s79, v138
	v_lshlrev_b32_e32 v251, 16, v106
	v_and_b32_e32 v252, s79, v106
	v_fmac_f32_e32 v243, v105, v105
	v_fmac_f32_e32 v224, v137, v137
	v_fma_f32 v106, -s26, v249, v251
	v_fma_f32 v138, -s26, v250, v252
	v_lshlrev_b32_e32 v249, 16, v139
	v_and_b32_e32 v250, s79, v139
	v_lshlrev_b32_e32 v251, 16, v107
	v_and_b32_e32 v252, s79, v107
	v_fmac_f32_e32 v243, v106, v106
	v_fmac_f32_e32 v224, v138, v138
	v_fma_f32 v107, -s26, v249, v251
	v_fma_f32 v139, -s26, v250, v252
	s_nop 0
	v_fmac_f32_e32 v243, v107, v107
	v_fmac_f32_e32 v224, v139, v139
	v_lshlrev_b32_e32 v249, 16, v140
	v_and_b32_e32 v250, s79, v140
; __device__ __forceinline__ float lane_xor(float v, int lane, int o) { return __int_as_float(__builtin_amdgcn_ds_bpermute((lane ^ o) << 2, __float_as_int(v))); }
; __device__ __forceinline__ float bflo(unsigned w) { return __uint_as_float(w << 16); }
; __device__ __forceinline__ float bfhi(unsigned w) { return __uint_as_float(w & 0xffff0000u); }
; __global__ void __launch_bounds__(NWAVES * 64, 2) fwd_kernel(Args args) {
;     ...
;                         for (int it = 0; it < 8; ++it) { const size_t row = r0 + it * 4; const v4u p = pp[it], q = qq[it], z = zz[it];
;                             float d[8]; float ss = 0.f;
; #pragma unroll
;                             for (int e = 0; e < 4; ++e) { d[2 * e] = bflo(p[e]) - lam * bflo(q[e]); d[2 * e + 1] = bfhi(p[e]) - lam * bfhi(q[e]); ss += d[2 * e] * d[2 * e] + d[2 * e + 1] * d[2 * e + 1]; }
;                             ss += lane_xor(ss, ln, 1); ss += lane_xor(ss, ln, 2); ss += lane_xor(ss, ln, 4); ss += lane_xor(ss, ln, 8);
	v_lshlrev_b32_e32 v251, 16, v108
	v_and_b32_e32 v252, s79, v108
	v_fma_f32 v108, -s26, v249, v251
	v_fma_f32 v140, -s26, v250, v252
	v_lshlrev_b32_e32 v249, 16, v141
	v_and_b32_e32 v250, s79, v141
	v_lshlrev_b32_e32 v251, 16, v109
	v_and_b32_e32 v252, s79, v109
	v_mul_f32_e32 v244, v108, v108
	v_mul_f32_e32 v225, v140, v140
	v_fma_f32 v109, -s26, v249, v251
	v_fma_f32 v141, -s26, v250, v252
	v_lshlrev_b32_e32 v249, 16, v142
	v_and_b32_e32 v250, s79, v142
	v_lshlrev_b32_e32 v251, 16, v110
	v_and_b32_e32 v252, s79, v110
	v_fmac_f32_e32 v244, v109, v109
	v_fmac_f32_e32 v225, v141, v141
	v_fma_f32 v110, -s26, v249, v251
	v_fma_f32 v142, -s26, v250, v252
	v_lshlrev_b32_e32 v249, 16, v143
	v_and_b32_e32 v250, s79, v143
	v_lshlrev_b32_e32 v251, 16, v111
	v_and_b32_e32 v252, s79, v111
	v_fmac_f32_e32 v244, v110, v110
	v_fmac_f32_e32 v225, v142, v142
	v_fma_f32 v111, -s26, v249, v251
	v_fma_f32 v143, -s26, v250, v252
	s_nop 0
	v_fmac_f32_e32 v244, v111, v111
	v_fmac_f32_e32 v225, v143, v143
	v_lshlrev_b32_e32 v249, 16, v144
	v_and_b32_e32 v250, s79, v144
	v_lshlrev_b32_e32 v251, 16, v112
	v_and_b32_e32 v252, s79, v112
	v_fma_f32 v112, -s26, v249, v251
	v_fma_f32 v144, -s26, v250, v252
	v_lshlrev_b32_e32 v249, 16, v145
	v_and_b32_e32 v250, s79, v145
	v_lshlrev_b32_e32 v251, 16, v113
	v_and_b32_e32 v252, s79, v113
	v_mul_f32_e32 v245, v112, v112
	v_mul_f32_e32 v226, v144, v144
	v_fma_f32 v113, -s26, v249, v251
	v_fma_f32 v145, -s26, v250, v252
	v_lshlrev_b32_e32 v249, 16, v146
	v_and_b32_e32 v250, s79, v146
	v_lshlrev_b32_e32 v251, 16, v114
	v_and_b32_e32 v252, s79, v114
	v_fmac_f32_e32 v245, v113, v113
	v_fmac_f32_e32 v226, v145, v145
	v_fma_f32 v114, -s26, v249, v251
	v_fma_f32 v146, -s26, v250, v252
	v_lshlrev_b32_e32 v249, 16, v147
	v_and_b32_e32 v250, s79, v147
	v_lshlrev_b32_e32 v251, 16, v115
	v_and_b32_e32 v252, s79, v115
	v_fmac_f32_e32 v245, v114, v114
	v_fmac_f32_e32 v226, v146, v146
	v_fma_f32 v115, -s26, v249, v251
	v_fma_f32 v147, -s26, v250, v252
	s_nop 0
	v_fmac_f32_e32 v245, v115, v115
	v_fmac_f32_e32 v226, v147, v147
	v_lshlrev_b32_e32 v249, 16, v148
	v_and_b32_e32 v250, s79, v148
	v_lshlrev_b32_e32 v251, 16, v116
	v_and_b32_e32 v252, s79, v116
	v_fma_f32 v116, -s26, v249, v251
	v_fma_f32 v148, -s26, v250, v252
	v_lshlrev_b32_e32 v249, 16, v149
	v_and_b32_e32 v250, s79, v149
	v_lshlrev_b32_e32 v251, 16, v117
	v_and_b32_e32 v252, s79, v117
	v_mul_f32_e32 v246, v116, v116
	v_mul_f32_e32 v227, v148, v148
	v_fma_f32 v117, -s26, v249, v251
	v_fma_f32 v149, -s26, v250, v252
	v_lshlrev_b32_e32 v249, 16, v150
	v_and_b32_e32 v250, s79, v150
	v_lshlrev_b32_e32 v251, 16, v118
	v_and_b32_e32 v252, s79, v118
	v_fmac_f32_e32 v246, v117, v117
	v_fmac_f32_e32 v227, v149, v149
	v_fma_f32 v118, -s26, v249, v251
	v_fma_f32 v150, -s26, v250, v252
	v_lshlrev_b32_e32 v249, 16, v151
	v_and_b32_e32 v250, s79, v151
	v_lshlrev_b32_e32 v251, 16, v119
	v_and_b32_e32 v252, s79, v119
	v_fmac_f32_e32 v246, v118, v118
	v_fmac_f32_e32 v227, v150, v150
	v_fma_f32 v119, -s26, v249, v251
	v_fma_f32 v151, -s26, v250, v252
	s_nop 0
	v_fmac_f32_e32 v246, v119, v119
	v_fmac_f32_e32 v227, v151, v151
	v_lshlrev_b32_e32 v249, 16, v152
	v_and_b32_e32 v250, s79, v152
	v_lshlrev_b32_e32 v251, 16, v120
	v_and_b32_e32 v252, s79, v120
	v_fma_f32 v120, -s26, v249, v251
	v_fma_f32 v152, -s26, v250, v252
	v_lshlrev_b32_e32 v249, 16, v153
	v_and_b32_e32 v250, s79, v153
	v_lshlrev_b32_e32 v251, 16, v121
	v_and_b32_e32 v252, s79, v121
	v_mul_f32_e32 v247, v120, v120
	v_mul_f32_e32 v228, v152, v152
	v_fma_f32 v121, -s26, v249, v251
	v_fma_f32 v153, -s26, v250, v252
	v_lshlrev_b32_e32 v249, 16, v154
	v_and_b32_e32 v250, s79, v154
	v_lshlrev_b32_e32 v251, 16, v122
	v_and_b32_e32 v252, s79, v122
	v_fmac_f32_e32 v247, v121, v121
	v_fmac_f32_e32 v228, v153, v153
	v_fma_f32 v122, -s26, v249, v251
	v_fma_f32 v154, -s26, v250, v252
	v_lshlrev_b32_e32 v249, 16, v155
	v_and_b32_e32 v250, s79, v155
	v_lshlrev_b32_e32 v251, 16, v123
	v_and_b32_e32 v252, s79, v123
	v_fmac_f32_e32 v247, v122, v122
	v_fmac_f32_e32 v228, v154, v154
	v_fma_f32 v123, -s26, v249, v251
	v_fma_f32 v155, -s26, v250, v252
	s_nop 0
	v_fmac_f32_e32 v247, v123, v123
	v_fmac_f32_e32 v228, v155, v155
	v_lshlrev_b32_e32 v249, 16, v156
	v_and_b32_e32 v250, s79, v156
	v_lshlrev_b32_e32 v251, 16, v124
	v_and_b32_e32 v252, s79, v124
	v_fma_f32 v124, -s26, v249, v251
	v_fma_f32 v156, -s26, v250, v252
	v_lshlrev_b32_e32 v249, 16, v157
	v_and_b32_e32 v250, s79, v157
	v_lshlrev_b32_e32 v251, 16, v125
	v_and_b32_e32 v252, s79, v125
	v_mul_f32_e32 v248, v124, v124
	v_mul_f32_e32 v229, v156, v156
	v_fma_f32 v125, -s26, v249, v251
	v_fma_f32 v157, -s26, v250, v252
	v_lshlrev_b32_e32 v249, 16, v158
	v_and_b32_e32 v250, s79, v158
	v_lshlrev_b32_e32 v251, 16, v126
	v_and_b32_e32 v252, s79, v126
	v_fmac_f32_e32 v248, v125, v125
	v_fmac_f32_e32 v229, v157, v157
	v_fma_f32 v126, -s26, v249, v251
	v_fma_f32 v158, -s26, v250, v252
	v_lshlrev_b32_e32 v249, 16, v159
	v_and_b32_e32 v250, s79, v159
	v_lshlrev_b32_e32 v251, 16, v127
	v_and_b32_e32 v252, s79, v127
	v_fmac_f32_e32 v248, v126, v126
	v_fmac_f32_e32 v229, v158, v158
	v_fma_f32 v127, -s26, v249, v251
	v_fma_f32 v159, -s26, v250, v252
	s_nop 0
	v_fmac_f32_e32 v248, v127, v127
	v_fmac_f32_e32 v229, v159, v159
	v_add_f32_e32 v241, v241, v222
	v_add_f32_e32 v242, v242, v223
	v_add_f32_e32 v243, v243, v224
	v_add_f32_e32 v244, v244, v225
	v_add_f32_e32 v245, v245, v226
	v_add_f32_e32 v246, v246, v227
	v_add_f32_e32 v247, v247, v228
	v_add_f32_e32 v248, v248, v229
	v_add_f32_dpp v241, v241, v241 quad_perm:[1,0,3,2] row_mask:0xf bank_mask:0xf
	v_add_f32_dpp v242, v242, v242 quad_perm:[1,0,3,2] row_mask:0xf bank_mask:0xf
; #define GASP __attribute__((address_space(1)))
; __device__ __forceinline__ float lane_xor(float v, int lane, int o) { return __int_as_float(__builtin_amdgcn_ds_bpermute((lane ^ o) << 2, __float_as_int(v))); }
; __device__ __forceinline__ unsigned pk2(float lo, float hi) { return f2bf(lo) | (f2bf(hi) << 16); }
; __device__ __forceinline__ float bflo(unsigned w) { return __uint_as_float(w << 16); }
; __device__ __forceinline__ float bfhi(unsigned w) { return __uint_as_float(w & 0xffff0000u); }
; __global__ void __launch_bounds__(NWAVES * 64, 2) fwd_kernel(Args args) {
;     ...
;                             ss += lane_xor(ss, ln, 1); ss += lane_xor(ss, ln, 2); ss += lane_xor(ss, ln, 4); ss += lane_xor(ss, ln, 8);
;                             const float r = 1.0f / sqrtf(ss * (1.f / 128.f) + 1e-6f);
;                             v4u o;
;                             o[0] = pk2(d[0] * r * sg0[0] * bflo(z[0]), d[1] * r * sg0[1] * bfhi(z[0])); o[1] = pk2(d[2] * r * sg0[2] * bflo(z[1]), d[3] * r * sg0[3] * bfhi(z[1]));
;                             o[2] = pk2(d[4] * r * sg1[0] * bflo(z[2]), d[5] * r * sg1[1] * bfhi(z[2])); o[3] = pk2(d[6] * r * sg1[2] * bflo(z[3]), d[7] * r * sg1[3] * bfhi(z[3]));
;                             *(GASP v4u*)(YCAT + row * 2048 + 1024 + h * 128 + c8) = o; }
	v_add_f32_dpp v243, v243, v243 quad_perm:[1,0,3,2] row_mask:0xf bank_mask:0xf
	v_add_f32_dpp v244, v244, v244 quad_perm:[1,0,3,2] row_mask:0xf bank_mask:0xf
	v_add_f32_dpp v245, v245, v245 quad_perm:[1,0,3,2] row_mask:0xf bank_mask:0xf
	v_add_f32_dpp v246, v246, v246 quad_perm:[1,0,3,2] row_mask:0xf bank_mask:0xf
	v_add_f32_dpp v247, v247, v247 quad_perm:[1,0,3,2] row_mask:0xf bank_mask:0xf
	v_add_f32_dpp v248, v248, v248 quad_perm:[1,0,3,2] row_mask:0xf bank_mask:0xf
	v_add_f32_dpp v241, v241, v241 quad_perm:[2,3,0,1] row_mask:0xf bank_mask:0xf
	v_add_f32_dpp v242, v242, v242 quad_perm:[2,3,0,1] row_mask:0xf bank_mask:0xf
	v_add_f32_dpp v243, v243, v243 quad_perm:[2,3,0,1] row_mask:0xf bank_mask:0xf
	v_add_f32_dpp v244, v244, v244 quad_perm:[2,3,0,1] row_mask:0xf bank_mask:0xf
	v_add_f32_dpp v245, v245, v245 quad_perm:[2,3,0,1] row_mask:0xf bank_mask:0xf
	v_add_f32_dpp v246, v246, v246 quad_perm:[2,3,0,1] row_mask:0xf bank_mask:0xf
	v_add_f32_dpp v247, v247, v247 quad_perm:[2,3,0,1] row_mask:0xf bank_mask:0xf
	v_add_f32_dpp v248, v248, v248 quad_perm:[2,3,0,1] row_mask:0xf bank_mask:0xf
	v_add_f32_dpp v241, v241, v241 row_ror:4 row_mask:0xf bank_mask:0xf
	v_add_f32_dpp v242, v242, v242 row_ror:4 row_mask:0xf bank_mask:0xf
	v_add_f32_dpp v243, v243, v243 row_ror:4 row_mask:0xf bank_mask:0xf
	v_add_f32_dpp v244, v244, v244 row_ror:4 row_mask:0xf bank_mask:0xf
	v_add_f32_dpp v245, v245, v245 row_ror:4 row_mask:0xf bank_mask:0xf
	v_add_f32_dpp v246, v246, v246 row_ror:4 row_mask:0xf bank_mask:0xf
	v_add_f32_dpp v247, v247, v247 row_ror:4 row_mask:0xf bank_mask:0xf
	v_add_f32_dpp v248, v248, v248 row_ror:4 row_mask:0xf bank_mask:0xf
	v_add_f32_dpp v241, v241, v241 row_ror:8 row_mask:0xf bank_mask:0xf
	v_add_f32_dpp v242, v242, v242 row_ror:8 row_mask:0xf bank_mask:0xf
	v_add_f32_dpp v243, v243, v243 row_ror:8 row_mask:0xf bank_mask:0xf
	v_add_f32_dpp v244, v244, v244 row_ror:8 row_mask:0xf bank_mask:0xf
	v_add_f32_dpp v245, v245, v245 row_ror:8 row_mask:0xf bank_mask:0xf
	v_add_f32_dpp v246, v246, v246 row_ror:8 row_mask:0xf bank_mask:0xf
	v_add_f32_dpp v247, v247, v247 row_ror:8 row_mask:0xf bank_mask:0xf
	v_add_f32_dpp v248, v248, v248 row_ror:8 row_mask:0xf bank_mask:0xf
	v_fmamk_f32 v241, v241, 0x3c000000, v231
	v_fmamk_f32 v242, v242, 0x3c000000, v231
	v_fmamk_f32 v243, v243, 0x3c000000, v231
	v_fmamk_f32 v244, v244, 0x3c000000, v231
	v_fmamk_f32 v245, v245, 0x3c000000, v231
	v_fmamk_f32 v246, v246, 0x3c000000, v231
	v_fmamk_f32 v247, v247, 0x3c000000, v231
	v_fmamk_f32 v248, v248, 0x3c000000, v231
	v_rsq_f32_e32 v241, v241
	v_rsq_f32_e32 v242, v242
	v_rsq_f32_e32 v243, v243
	v_rsq_f32_e32 v244, v244
	v_rsq_f32_e32 v245, v245
	v_rsq_f32_e32 v246, v246
	v_rsq_f32_e32 v247, v247
	v_rsq_f32_e32 v248, v248
	v_lshlrev_b32_e32 v249, 16, v160
	v_and_b32_e32 v250, s79, v160
	v_mul_f32_e32 v96, v96, v241
	v_mul_f32_e32 v128, v128, v241
	v_mul_f32_e32 v96, v96, v192
	v_mul_f32_e32 v128, v128, v193
	v_mul_f32_e32 v96, v96, v249
	v_mul_f32_e32 v128, v128, v250
	v_cvt_pk_bf16_f32 v160, v96, v128
	v_lshlrev_b32_e32 v251, 16, v161
	v_and_b32_e32 v252, s79, v161
	v_mul_f32_e32 v97, v97, v241
	v_mul_f32_e32 v129, v129, v241
	v_mul_f32_e32 v97, v97, v194
	v_mul_f32_e32 v129, v129, v195
	v_mul_f32_e32 v97, v97, v251
	v_mul_f32_e32 v129, v129, v252
	v_cvt_pk_bf16_f32 v161, v97, v129
	v_lshlrev_b32_e32 v249, 16, v162
	v_and_b32_e32 v250, s79, v162
	v_mul_f32_e32 v98, v98, v241
	v_mul_f32_e32 v130, v130, v241
	v_mul_f32_e32 v98, v98, v196
	v_mul_f32_e32 v130, v130, v197
	v_mul_f32_e32 v98, v98, v249
	v_mul_f32_e32 v130, v130, v250
	v_cvt_pk_bf16_f32 v162, v98, v130
	v_lshlrev_b32_e32 v251, 16, v163
	v_and_b32_e32 v252, s79, v163
	v_mul_f32_e32 v99, v99, v241
	v_mul_f32_e32 v131, v131, v241
	v_mul_f32_e32 v99, v99, v198
	v_mul_f32_e32 v131, v131, v199
	v_mul_f32_e32 v99, v99, v251
	v_mul_f32_e32 v131, v131, v252
	v_cvt_pk_bf16_f32 v163, v99, v131
	global_store_dwordx4 v209, v[160:163], s[28:29]
	v_lshlrev_b32_e32 v249, 16, v164
	v_and_b32_e32 v250, s79, v164
	v_mul_f32_e32 v100, v100, v242
	v_mul_f32_e32 v132, v132, v242
	v_mul_f32_e32 v100, v100, v192
	v_mul_f32_e32 v132, v132, v193
	v_mul_f32_e32 v100, v100, v249
	v_mul_f32_e32 v132, v132, v250
	v_cvt_pk_bf16_f32 v164, v100, v132
	v_lshlrev_b32_e32 v251, 16, v165
	v_and_b32_e32 v252, s79, v165
	v_mul_f32_e32 v101, v101, v242
	v_mul_f32_e32 v133, v133, v242
	v_mul_f32_e32 v101, v101, v194
	v_mul_f32_e32 v133, v133, v195
	v_mul_f32_e32 v101, v101, v251
	v_mul_f32_e32 v133, v133, v252
	v_cvt_pk_bf16_f32 v165, v101, v133
	v_lshlrev_b32_e32 v249, 16, v166
	v_and_b32_e32 v250, s79, v166
	v_mul_f32_e32 v102, v102, v242
	v_mul_f32_e32 v134, v134, v242
	v_mul_f32_e32 v102, v102, v196
	v_mul_f32_e32 v134, v134, v197
	v_mul_f32_e32 v102, v102, v249
	v_mul_f32_e32 v134, v134, v250
	v_cvt_pk_bf16_f32 v166, v102, v134
	v_lshlrev_b32_e32 v251, 16, v167
	v_and_b32_e32 v252, s79, v167
	v_mul_f32_e32 v103, v103, v242
	v_mul_f32_e32 v135, v135, v242
	v_mul_f32_e32 v103, v103, v198
	v_mul_f32_e32 v135, v135, v199
	v_mul_f32_e32 v103, v103, v251
	v_mul_f32_e32 v135, v135, v252
	v_cvt_pk_bf16_f32 v167, v103, v135
	global_store_dwordx4 v210, v[164:167], s[28:29]
	v_lshlrev_b32_e32 v249, 16, v168
	v_and_b32_e32 v250, s79, v168
	v_mul_f32_e32 v104, v104, v243
	v_mul_f32_e32 v136, v136, v243
	v_mul_f32_e32 v104, v104, v192
	v_mul_f32_e32 v136, v136, v193
	v_mul_f32_e32 v104, v104, v249
	v_mul_f32_e32 v136, v136, v250
	v_cvt_pk_bf16_f32 v168, v104, v136
	v_lshlrev_b32_e32 v251, 16, v169
	v_and_b32_e32 v252, s79, v169
	v_mul_f32_e32 v105, v105, v243
	v_mul_f32_e32 v137, v137, v243
	v_mul_f32_e32 v105, v105, v194
	v_mul_f32_e32 v137, v137, v195
; #define GASP __attribute__((address_space(1)))
; __device__ __forceinline__ unsigned pk2(float lo, float hi) { return f2bf(lo) | (f2bf(hi) << 16); }
; __device__ __forceinline__ float bflo(unsigned w) { return __uint_as_float(w << 16); }
; __device__ __forceinline__ float bfhi(unsigned w) { return __uint_as_float(w & 0xffff0000u); }
; __global__ void __launch_bounds__(NWAVES * 64, 2) fwd_kernel(Args args) {
;     ...
;                             o[0] = pk2(d[0] * r * sg0[0] * bflo(z[0]), d[1] * r * sg0[1] * bfhi(z[0])); o[1] = pk2(d[2] * r * sg0[2] * bflo(z[1]), d[3] * r * sg0[3] * bfhi(z[1]));
;                             o[2] = pk2(d[4] * r * sg1[0] * bflo(z[2]), d[5] * r * sg1[1] * bfhi(z[2])); o[3] = pk2(d[6] * r * sg1[2] * bflo(z[3]), d[7] * r * sg1[3] * bfhi(z[3]));
;                             *(GASP v4u*)(YCAT + row * 2048 + 1024 + h * 128 + c8) = o; }
	v_mul_f32_e32 v105, v105, v251
	v_mul_f32_e32 v137, v137, v252
	v_cvt_pk_bf16_f32 v169, v105, v137
	v_lshlrev_b32_e32 v249, 16, v170
	v_and_b32_e32 v250, s79, v170
	v_mul_f32_e32 v106, v106, v243
	v_mul_f32_e32 v138, v138, v243
	v_mul_f32_e32 v106, v106, v196
	v_mul_f32_e32 v138, v138, v197
	v_mul_f32_e32 v106, v106, v249
	v_mul_f32_e32 v138, v138, v250
	v_cvt_pk_bf16_f32 v170, v106, v138
	v_lshlrev_b32_e32 v251, 16, v171
	v_and_b32_e32 v252, s79, v171
	v_mul_f32_e32 v107, v107, v243
	v_mul_f32_e32 v139, v139, v243
	v_mul_f32_e32 v107, v107, v198
	v_mul_f32_e32 v139, v139, v199
	v_mul_f32_e32 v107, v107, v251
	v_mul_f32_e32 v139, v139, v252
	v_cvt_pk_bf16_f32 v171, v107, v139
	global_store_dwordx4 v211, v[168:171], s[28:29]
	v_lshlrev_b32_e32 v249, 16, v172
	v_and_b32_e32 v250, s79, v172
	v_mul_f32_e32 v108, v108, v244
	v_mul_f32_e32 v140, v140, v244
	v_mul_f32_e32 v108, v108, v192
	v_mul_f32_e32 v140, v140, v193
	v_mul_f32_e32 v108, v108, v249
	v_mul_f32_e32 v140, v140, v250
	v_cvt_pk_bf16_f32 v172, v108, v140
	v_lshlrev_b32_e32 v251, 16, v173
	v_and_b32_e32 v252, s79, v173
	v_mul_f32_e32 v109, v109, v244
	v_mul_f32_e32 v141, v141, v244
	v_mul_f32_e32 v109, v109, v194
	v_mul_f32_e32 v141, v141, v195
	v_mul_f32_e32 v109, v109, v251
	v_mul_f32_e32 v141, v141, v252
	v_cvt_pk_bf16_f32 v173, v109, v141
	v_lshlrev_b32_e32 v249, 16, v174
	v_and_b32_e32 v250, s79, v174
	v_mul_f32_e32 v110, v110, v244
	v_mul_f32_e32 v142, v142, v244
	v_mul_f32_e32 v110, v110, v196
	v_mul_f32_e32 v142, v142, v197
	v_mul_f32_e32 v110, v110, v249
	v_mul_f32_e32 v142, v142, v250
	v_cvt_pk_bf16_f32 v174, v110, v142
	v_lshlrev_b32_e32 v251, 16, v175
	v_and_b32_e32 v252, s79, v175
	v_mul_f32_e32 v111, v111, v244
	v_mul_f32_e32 v143, v143, v244
	v_mul_f32_e32 v111, v111, v198
	v_mul_f32_e32 v143, v143, v199
	v_mul_f32_e32 v111, v111, v251
	v_mul_f32_e32 v143, v143, v252
	v_cvt_pk_bf16_f32 v175, v111, v143
	global_store_dwordx4 v214, v[172:175], s[28:29]
	v_lshlrev_b32_e32 v249, 16, v176
	v_and_b32_e32 v250, s79, v176
	v_mul_f32_e32 v112, v112, v245
	v_mul_f32_e32 v144, v144, v245
	v_mul_f32_e32 v112, v112, v192
	v_mul_f32_e32 v144, v144, v193
	v_mul_f32_e32 v112, v112, v249
	v_mul_f32_e32 v144, v144, v250
	v_cvt_pk_bf16_f32 v176, v112, v144
	v_lshlrev_b32_e32 v251, 16, v177
	v_and_b32_e32 v252, s79, v177
	v_mul_f32_e32 v113, v113, v245
	v_mul_f32_e32 v145, v145, v245
	v_mul_f32_e32 v113, v113, v194
	v_mul_f32_e32 v145, v145, v195
	v_mul_f32_e32 v113, v113, v251
	v_mul_f32_e32 v145, v145, v252
	v_cvt_pk_bf16_f32 v177, v113, v145
	v_lshlrev_b32_e32 v249, 16, v178
	v_and_b32_e32 v250, s79, v178
	v_mul_f32_e32 v114, v114, v245
	v_mul_f32_e32 v146, v146, v245
	v_mul_f32_e32 v114, v114, v196
	v_mul_f32_e32 v146, v146, v197
	v_mul_f32_e32 v114, v114, v249
	v_mul_f32_e32 v146, v146, v250
	v_cvt_pk_bf16_f32 v178, v114, v146
	v_lshlrev_b32_e32 v251, 16, v179
	v_and_b32_e32 v252, s79, v179
	v_mul_f32_e32 v115, v115, v245
	v_mul_f32_e32 v147, v147, v245
	v_mul_f32_e32 v115, v115, v198
	v_mul_f32_e32 v147, v147, v199
	v_mul_f32_e32 v115, v115, v251
	v_mul_f32_e32 v147, v147, v252
	v_cvt_pk_bf16_f32 v179, v115, v147
	global_store_dwordx4 v215, v[176:179], s[28:29]
	v_lshlrev_b32_e32 v249, 16, v180
	v_and_b32_e32 v250, s79, v180
	v_mul_f32_e32 v116, v116, v246
	v_mul_f32_e32 v148, v148, v246
	v_mul_f32_e32 v116, v116, v192
	v_mul_f32_e32 v148, v148, v193
	v_mul_f32_e32 v116, v116, v249
	v_mul_f32_e32 v148, v148, v250
	v_cvt_pk_bf16_f32 v180, v116, v148
	v_lshlrev_b32_e32 v251, 16, v181
	v_and_b32_e32 v252, s79, v181
	v_mul_f32_e32 v117, v117, v246
	v_mul_f32_e32 v149, v149, v246
	v_mul_f32_e32 v117, v117, v194
	v_mul_f32_e32 v149, v149, v195
	v_mul_f32_e32 v117, v117, v251
	v_mul_f32_e32 v149, v149, v252
	v_cvt_pk_bf16_f32 v181, v117, v149
	v_lshlrev_b32_e32 v249, 16, v182
	v_and_b32_e32 v250, s79, v182
	v_mul_f32_e32 v118, v118, v246
	v_mul_f32_e32 v150, v150, v246
	v_mul_f32_e32 v118, v118, v196
	v_mul_f32_e32 v150, v150, v197
	v_mul_f32_e32 v118, v118, v249
	v_mul_f32_e32 v150, v150, v250
	v_cvt_pk_bf16_f32 v182, v118, v150
	v_lshlrev_b32_e32 v251, 16, v183
	v_and_b32_e32 v252, s79, v183
	v_mul_f32_e32 v119, v119, v246
	v_mul_f32_e32 v151, v151, v246
	v_mul_f32_e32 v119, v119, v198
	v_mul_f32_e32 v151, v151, v199
	v_mul_f32_e32 v119, v119, v251
	v_mul_f32_e32 v151, v151, v252
	v_cvt_pk_bf16_f32 v183, v119, v151
	global_store_dwordx4 v216, v[180:183], s[28:29]
	v_lshlrev_b32_e32 v249, 16, v184
	v_and_b32_e32 v250, s79, v184
	v_mul_f32_e32 v120, v120, v247
	v_mul_f32_e32 v152, v152, v247
	v_mul_f32_e32 v120, v120, v192
	v_mul_f32_e32 v152, v152, v193
	v_mul_f32_e32 v120, v120, v249
	v_mul_f32_e32 v152, v152, v250
	v_cvt_pk_bf16_f32 v184, v120, v152
	v_lshlrev_b32_e32 v251, 16, v185
	v_and_b32_e32 v252, s79, v185
	v_mul_f32_e32 v121, v121, v247
	v_mul_f32_e32 v153, v153, v247
	v_mul_f32_e32 v121, v121, v194
	v_mul_f32_e32 v153, v153, v195
	v_mul_f32_e32 v121, v121, v251
	v_mul_f32_e32 v153, v153, v252
	v_cvt_pk_bf16_f32 v185, v121, v153
	v_lshlrev_b32_e32 v249, 16, v186
	v_and_b32_e32 v250, s79, v186
	v_mul_f32_e32 v122, v122, v247
	v_mul_f32_e32 v154, v154, v247
	v_mul_f32_e32 v122, v122, v196
	v_mul_f32_e32 v154, v154, v197
	v_mul_f32_e32 v122, v122, v249
	v_mul_f32_e32 v154, v154, v250
	v_cvt_pk_bf16_f32 v186, v122, v154
	v_lshlrev_b32_e32 v251, 16, v187
	v_and_b32_e32 v252, s79, v187
	v_mul_f32_e32 v123, v123, v247
	v_mul_f32_e32 v155, v155, v247
	v_mul_f32_e32 v123, v123, v198
	v_mul_f32_e32 v155, v155, v199
	v_mul_f32_e32 v123, v123, v251
	v_mul_f32_e32 v155, v155, v252
	v_cvt_pk_bf16_f32 v187, v123, v155
	global_store_dwordx4 v217, v[184:187], s[28:29]
	v_lshlrev_b32_e32 v249, 16, v188
; #define GASP __attribute__((address_space(1)))
; __device__ __forceinline__ float lane_xor(float v, int lane, int o) { return __int_as_float(__builtin_amdgcn_ds_bpermute((lane ^ o) << 2, __float_as_int(v))); }
; __device__ __forceinline__ unsigned pk2(float lo, float hi) { return f2bf(lo) | (f2bf(hi) << 16); }
; __device__ __forceinline__ float bflo(unsigned w) { return __uint_as_float(w << 16); }
; __device__ __forceinline__ float bfhi(unsigned w) { return __uint_as_float(w & 0xffff0000u); }
; __global__ void __launch_bounds__(NWAVES * 64, 2) fwd_kernel(Args args) {
;     ...
;                         const size_t r0 = (size_t)b * SEQ + qb * 256 + wave * 32 + sub;
;                         const bf16* O1 = (const bf16*)(w2 + WS_H); const bf16* O2 = O1 + (size_t)NTOK * 1024; const bf16* ZA = (const bf16*)(w2 + WS_ZA); bf16* YCAT = (bf16*)(w2 + WS_A2);
;                         v4u pp[8], qq[8], zz[8];
; #pragma unroll
;                         for (int it = 0; it < 8; ++it) { const size_t off = (r0 + it * 4) * 1024 + h * 128 + c8;
;                             pp[it] = *(const GASP v4u*)(O1 + off); qq[it] = *(const GASP v4u*)(O2 + off);
;                             zz[it] = *(const GASP v4u*)(ZA + off); }
; #pragma unroll
;                         for (int it = 0; it < 8; ++it) { const size_t row = r0 + it * 4; const v4u p = pp[it], q = qq[it], z = zz[it];
;                             float d[8]; float ss = 0.f;
; #pragma unroll
;                             for (int e = 0; e < 4; ++e) { d[2 * e] = bflo(p[e]) - lam * bflo(q[e]); d[2 * e + 1] = bfhi(p[e]) - lam * bfhi(q[e]); ss += d[2 * e] * d[2 * e] + d[2 * e + 1] * d[2 * e + 1]; }
;                             ss += lane_xor(ss, ln, 1); ss += lane_xor(ss, ln, 2); ss += lane_xor(ss, ln, 4); ss += lane_xor(ss, ln, 8);
;                             const float r = 1.0f / sqrtf(ss * (1.f / 128.f) + 1e-6f);
;                             v4u o;
;                             o[0] = pk2(d[0] * r * sg0[0] * bflo(z[0]), d[1] * r * sg0[1] * bfhi(z[0])); o[1] = pk2(d[2] * r * sg0[2] * bflo(z[1]), d[3] * r * sg0[3] * bfhi(z[1]));
;                             o[2] = pk2(d[4] * r * sg1[0] * bflo(z[2]), d[5] * r * sg1[1] * bfhi(z[2])); o[3] = pk2(d[6] * r * sg1[2] * bflo(z[3]), d[7] * r * sg1[3] * bfhi(z[3]));
;                             *(GASP v4u*)(YCAT + row * 2048 + 1024 + h * 128 + c8) = o; }
	v_and_b32_e32 v250, s79, v188
	v_mul_f32_e32 v124, v124, v248
	v_mul_f32_e32 v156, v156, v248
	v_mul_f32_e32 v124, v124, v192
	v_mul_f32_e32 v156, v156, v193
	v_mul_f32_e32 v124, v124, v249
	v_mul_f32_e32 v156, v156, v250
	v_cvt_pk_bf16_f32 v188, v124, v156
	v_lshlrev_b32_e32 v251, 16, v189
	v_and_b32_e32 v252, s79, v189
	v_mul_f32_e32 v125, v125, v248
	v_mul_f32_e32 v157, v157, v248
	v_mul_f32_e32 v125, v125, v194
	v_mul_f32_e32 v157, v157, v195
	v_mul_f32_e32 v125, v125, v251
	v_mul_f32_e32 v157, v157, v252
	v_cvt_pk_bf16_f32 v189, v125, v157
	v_lshlrev_b32_e32 v249, 16, v190
	v_and_b32_e32 v250, s79, v190
	v_mul_f32_e32 v126, v126, v248
	v_mul_f32_e32 v158, v158, v248
	v_mul_f32_e32 v126, v126, v196
	v_mul_f32_e32 v158, v158, v197
	v_mul_f32_e32 v126, v126, v249
	v_mul_f32_e32 v158, v158, v250
	v_cvt_pk_bf16_f32 v190, v126, v158
	v_lshlrev_b32_e32 v251, 16, v191
	v_and_b32_e32 v252, s79, v191
	v_mul_f32_e32 v127, v127, v248
	v_mul_f32_e32 v159, v159, v248
	v_mul_f32_e32 v127, v127, v198
	v_mul_f32_e32 v159, v159, v199
	v_mul_f32_e32 v127, v127, v251
	v_mul_f32_e32 v159, v159, v252
	v_cvt_pk_bf16_f32 v191, v127, v159
	global_store_dwordx4 v219, v[188:191], s[28:29]
	s_lshl_b32 s21, s75, 23
	s_lshl_b32 s32, s57, 19
	s_add_u32 s21, s21, s32
	s_lshl_b32 s32, s61, 1
	s_add_u32 s21, s21, s32
	s_add_u32 s21, s21, 0xda00000
	s_add_u32 s0, s8, s21
	s_addc_u32 s1, s9, 0
	s_add_u32 s4, s0, 0x4000000
	s_addc_u32 s5, s1, 0
	s_add_u32 s6, s0, 0x24000000
	s_addc_u32 s7, s1, 0
	global_load_dwordx4 v[96:99], v200, s[0:1]
	global_load_dwordx4 v[128:131], v200, s[4:5]
	global_load_dwordx4 v[100:103], v201, s[0:1]
	global_load_dwordx4 v[132:135], v201, s[4:5]
	global_load_dwordx4 v[104:107], v202, s[0:1]
	global_load_dwordx4 v[136:139], v202, s[4:5]
	global_load_dwordx4 v[108:111], v203, s[0:1]
	global_load_dwordx4 v[140:143], v203, s[4:5]
	global_load_dwordx4 v[112:115], v204, s[0:1]
	global_load_dwordx4 v[144:147], v204, s[4:5]
	global_load_dwordx4 v[116:119], v206, s[0:1]
	global_load_dwordx4 v[148:151], v206, s[4:5]
	global_load_dwordx4 v[120:123], v207, s[0:1]
	global_load_dwordx4 v[152:155], v207, s[4:5]
	global_load_dwordx4 v[124:127], v208, s[0:1]
	global_load_dwordx4 v[156:159], v208, s[4:5]
	global_load_dwordx4 v[160:163], v200, s[6:7]
	global_load_dwordx4 v[164:167], v201, s[6:7]
	global_load_dwordx4 v[168:171], v202, s[6:7]
	global_load_dwordx4 v[172:175], v203, s[6:7]
	global_load_dwordx4 v[176:179], v204, s[6:7]
	global_load_dwordx4 v[180:183], v206, s[6:7]
	global_load_dwordx4 v[184:187], v207, s[6:7]
	global_load_dwordx4 v[188:191], v208, s[6:7]
	s_lshl_b32 s21, s75, 24
	s_lshl_b32 s32, s60, 20
	s_add_u32 s21, s21, s32
	s_lshl_b32 s32, s61, 1
	s_add_u32 s21, s21, s32
	s_add_u32 s21, s21, 0x15a00800
	s_add_u32 s28, s8, s21
	s_addc_u32 s29, s9, 0
	s_waitcnt vmcnt(32)
	v_lshlrev_b32_e32 v249, 16, v32
	v_and_b32_e32 v250, s79, v32
	v_lshlrev_b32_e32 v251, 16, v0
	v_and_b32_e32 v252, s79, v0
	v_fma_f32 v0, -s26, v249, v251
	v_fma_f32 v32, -s26, v250, v252
	v_lshlrev_b32_e32 v249, 16, v33
	v_and_b32_e32 v250, s79, v33
	v_lshlrev_b32_e32 v251, 16, v1
	v_and_b32_e32 v252, s79, v1
	v_mul_f32_e32 v241, v0, v0
	v_mul_f32_e32 v222, v32, v32
	v_fma_f32 v1, -s26, v249, v251
	v_fma_f32 v33, -s26, v250, v252
	v_lshlrev_b32_e32 v249, 16, v34
	v_and_b32_e32 v250, s79, v34
	v_lshlrev_b32_e32 v251, 16, v2
	v_and_b32_e32 v252, s79, v2
	v_fmac_f32_e32 v241, v1, v1
	v_fmac_f32_e32 v222, v33, v33
	v_fma_f32 v2, -s26, v249, v251
	v_fma_f32 v34, -s26, v250, v252
	v_lshlrev_b32_e32 v249, 16, v35
	v_and_b32_e32 v250, s79, v35
	v_lshlrev_b32_e32 v251, 16, v3
	v_and_b32_e32 v252, s79, v3
	v_fmac_f32_e32 v241, v2, v2
	v_fmac_f32_e32 v222, v34, v34
	v_fma_f32 v3, -s26, v249, v251
	v_fma_f32 v35, -s26, v250, v252
	s_nop 0
	v_fmac_f32_e32 v241, v3, v3
	v_fmac_f32_e32 v222, v35, v35
	v_lshlrev_b32_e32 v249, 16, v36
	v_and_b32_e32 v250, s79, v36
	v_lshlrev_b32_e32 v251, 16, v4
	v_and_b32_e32 v252, s79, v4
	v_fma_f32 v4, -s26, v249, v251
	v_fma_f32 v36, -s26, v250, v252
	v_lshlrev_b32_e32 v249, 16, v37
	v_and_b32_e32 v250, s79, v37
	v_lshlrev_b32_e32 v251, 16, v5
	v_and_b32_e32 v252, s79, v5
	v_mul_f32_e32 v242, v4, v4
	v_mul_f32_e32 v223, v36, v36
	v_fma_f32 v5, -s26, v249, v251
	v_fma_f32 v37, -s26, v250, v252
	v_lshlrev_b32_e32 v249, 16, v38
	v_and_b32_e32 v250, s79, v38
	v_lshlrev_b32_e32 v251, 16, v6
	v_and_b32_e32 v252, s79, v6
	v_fmac_f32_e32 v242, v5, v5
	v_fmac_f32_e32 v223, v37, v37
	v_fma_f32 v6, -s26, v249, v251
	v_fma_f32 v38, -s26, v250, v252
	v_lshlrev_b32_e32 v249, 16, v39
	v_and_b32_e32 v250, s79, v39
	v_lshlrev_b32_e32 v251, 16, v7
	v_and_b32_e32 v252, s79, v7
	v_fmac_f32_e32 v242, v6, v6
	v_fmac_f32_e32 v223, v38, v38
	v_fma_f32 v7, -s26, v249, v251
	v_fma_f32 v39, -s26, v250, v252
	s_nop 0
	v_fmac_f32_e32 v242, v7, v7
	v_fmac_f32_e32 v223, v39, v39
	v_lshlrev_b32_e32 v249, 16, v40
	v_and_b32_e32 v250, s79, v40
	v_lshlrev_b32_e32 v251, 16, v8
	v_and_b32_e32 v252, s79, v8
	v_fma_f32 v8, -s26, v249, v251
	v_fma_f32 v40, -s26, v250, v252
	v_lshlrev_b32_e32 v249, 16, v41
	v_and_b32_e32 v250, s79, v41
	v_lshlrev_b32_e32 v251, 16, v9
	v_and_b32_e32 v252, s79, v9
	v_mul_f32_e32 v243, v8, v8
	v_mul_f32_e32 v224, v40, v40
	v_fma_f32 v9, -s26, v249, v251
	v_fma_f32 v41, -s26, v250, v252
	v_lshlrev_b32_e32 v249, 16, v42
	v_and_b32_e32 v250, s79, v42
	v_lshlrev_b32_e32 v251, 16, v10
	v_and_b32_e32 v252, s79, v10
	v_fmac_f32_e32 v243, v9, v9
	v_fmac_f32_e32 v224, v41, v41
	v_fma_f32 v10, -s26, v249, v251
	v_fma_f32 v42, -s26, v250, v252
	v_lshlrev_b32_e32 v249, 16, v43
	v_and_b32_e32 v250, s79, v43
	v_lshlrev_b32_e32 v251, 16, v11
	v_and_b32_e32 v252, s79, v11
; __device__ __forceinline__ float bflo(unsigned w) { return __uint_as_float(w << 16); }
; __device__ __forceinline__ float bfhi(unsigned w) { return __uint_as_float(w & 0xffff0000u); }
; __global__ void __launch_bounds__(NWAVES * 64, 2) fwd_kernel(Args args) {
;     ...
;                         for (int it = 0; it < 8; ++it) { const size_t row = r0 + it * 4; const v4u p = pp[it], q = qq[it], z = zz[it];
;                             float d[8]; float ss = 0.f;
; #pragma unroll
;                             for (int e = 0; e < 4; ++e) { d[2 * e] = bflo(p[e]) - lam * bflo(q[e]); d[2 * e + 1] = bfhi(p[e]) - lam * bfhi(q[e]); ss += d[2 * e] * d[2 * e] + d[2 * e + 1] * d[2 * e + 1]; }
	v_fmac_f32_e32 v243, v10, v10
	v_fmac_f32_e32 v224, v42, v42
	v_fma_f32 v11, -s26, v249, v251
	v_fma_f32 v43, -s26, v250, v252
	s_nop 0
	v_fmac_f32_e32 v243, v11, v11
	v_fmac_f32_e32 v224, v43, v43
	v_lshlrev_b32_e32 v249, 16, v44
	v_and_b32_e32 v250, s79, v44
	v_lshlrev_b32_e32 v251, 16, v12
	v_and_b32_e32 v252, s79, v12
	v_fma_f32 v12, -s26, v249, v251
	v_fma_f32 v44, -s26, v250, v252
	v_lshlrev_b32_e32 v249, 16, v45
	v_and_b32_e32 v250, s79, v45
	v_lshlrev_b32_e32 v251, 16, v13
	v_and_b32_e32 v252, s79, v13
	v_mul_f32_e32 v244, v12, v12
	v_mul_f32_e32 v225, v44, v44
	v_fma_f32 v13, -s26, v249, v251
	v_fma_f32 v45, -s26, v250, v252
	v_lshlrev_b32_e32 v249, 16, v46
	v_and_b32_e32 v250, s79, v46
	v_lshlrev_b32_e32 v251, 16, v14
	v_and_b32_e32 v252, s79, v14
	v_fmac_f32_e32 v244, v13, v13
	v_fmac_f32_e32 v225, v45, v45
	v_fma_f32 v14, -s26, v249, v251
	v_fma_f32 v46, -s26, v250, v252
	v_lshlrev_b32_e32 v249, 16, v47
	v_and_b32_e32 v250, s79, v47
	v_lshlrev_b32_e32 v251, 16, v15
	v_and_b32_e32 v252, s79, v15
	v_fmac_f32_e32 v244, v14, v14
	v_fmac_f32_e32 v225, v46, v46
	v_fma_f32 v15, -s26, v249, v251
	v_fma_f32 v47, -s26, v250, v252
	s_nop 0
	v_fmac_f32_e32 v244, v15, v15
	v_fmac_f32_e32 v225, v47, v47
	v_lshlrev_b32_e32 v249, 16, v48
	v_and_b32_e32 v250, s79, v48
	v_lshlrev_b32_e32 v251, 16, v16
	v_and_b32_e32 v252, s79, v16
	v_fma_f32 v16, -s26, v249, v251
	v_fma_f32 v48, -s26, v250, v252
	v_lshlrev_b32_e32 v249, 16, v49
	v_and_b32_e32 v250, s79, v49
	v_lshlrev_b32_e32 v251, 16, v17
	v_and_b32_e32 v252, s79, v17
	v_mul_f32_e32 v245, v16, v16
	v_mul_f32_e32 v226, v48, v48
	v_fma_f32 v17, -s26, v249, v251
	v_fma_f32 v49, -s26, v250, v252
	v_lshlrev_b32_e32 v249, 16, v50
	v_and_b32_e32 v250, s79, v50
	v_lshlrev_b32_e32 v251, 16, v18
	v_and_b32_e32 v252, s79, v18
	v_fmac_f32_e32 v245, v17, v17
	v_fmac_f32_e32 v226, v49, v49
	v_fma_f32 v18, -s26, v249, v251
	v_fma_f32 v50, -s26, v250, v252
	v_lshlrev_b32_e32 v249, 16, v51
	v_and_b32_e32 v250, s79, v51
	v_lshlrev_b32_e32 v251, 16, v19
	v_and_b32_e32 v252, s79, v19
	v_fmac_f32_e32 v245, v18, v18
	v_fmac_f32_e32 v226, v50, v50
	v_fma_f32 v19, -s26, v249, v251
	v_fma_f32 v51, -s26, v250, v252
	s_nop 0
	v_fmac_f32_e32 v245, v19, v19
	v_fmac_f32_e32 v226, v51, v51
	v_lshlrev_b32_e32 v249, 16, v52
	v_and_b32_e32 v250, s79, v52
	v_lshlrev_b32_e32 v251, 16, v20
	v_and_b32_e32 v252, s79, v20
	v_fma_f32 v20, -s26, v249, v251
	v_fma_f32 v52, -s26, v250, v252
	v_lshlrev_b32_e32 v249, 16, v53
	v_and_b32_e32 v250, s79, v53
	v_lshlrev_b32_e32 v251, 16, v21
	v_and_b32_e32 v252, s79, v21
	v_mul_f32_e32 v246, v20, v20
	v_mul_f32_e32 v227, v52, v52
	v_fma_f32 v21, -s26, v249, v251
	v_fma_f32 v53, -s26, v250, v252
	v_lshlrev_b32_e32 v249, 16, v54
	v_and_b32_e32 v250, s79, v54
	v_lshlrev_b32_e32 v251, 16, v22
	v_and_b32_e32 v252, s79, v22
	v_fmac_f32_e32 v246, v21, v21
	v_fmac_f32_e32 v227, v53, v53
	v_fma_f32 v22, -s26, v249, v251
	v_fma_f32 v54, -s26, v250, v252
	v_lshlrev_b32_e32 v249, 16, v55
	v_and_b32_e32 v250, s79, v55
	v_lshlrev_b32_e32 v251, 16, v23
	v_and_b32_e32 v252, s79, v23
	v_fmac_f32_e32 v246, v22, v22
	v_fmac_f32_e32 v227, v54, v54
	v_fma_f32 v23, -s26, v249, v251
	v_fma_f32 v55, -s26, v250, v252
	s_nop 0
	v_fmac_f32_e32 v246, v23, v23
	v_fmac_f32_e32 v227, v55, v55
	v_lshlrev_b32_e32 v249, 16, v56
	v_and_b32_e32 v250, s79, v56
	v_lshlrev_b32_e32 v251, 16, v24
	v_and_b32_e32 v252, s79, v24
	v_fma_f32 v24, -s26, v249, v251
	v_fma_f32 v56, -s26, v250, v252
	v_lshlrev_b32_e32 v249, 16, v57
	v_and_b32_e32 v250, s79, v57
	v_lshlrev_b32_e32 v251, 16, v25
	v_and_b32_e32 v252, s79, v25
	v_mul_f32_e32 v247, v24, v24
	v_mul_f32_e32 v228, v56, v56
	v_fma_f32 v25, -s26, v249, v251
	v_fma_f32 v57, -s26, v250, v252
	v_lshlrev_b32_e32 v249, 16, v58
	v_and_b32_e32 v250, s79, v58
	v_lshlrev_b32_e32 v251, 16, v26
	v_and_b32_e32 v252, s79, v26
	v_fmac_f32_e32 v247, v25, v25
	v_fmac_f32_e32 v228, v57, v57
	v_fma_f32 v26, -s26, v249, v251
	v_fma_f32 v58, -s26, v250, v252
	v_lshlrev_b32_e32 v249, 16, v59
	v_and_b32_e32 v250, s79, v59
	v_lshlrev_b32_e32 v251, 16, v27
	v_and_b32_e32 v252, s79, v27
	v_fmac_f32_e32 v247, v26, v26
	v_fmac_f32_e32 v228, v58, v58
	v_fma_f32 v27, -s26, v249, v251
	v_fma_f32 v59, -s26, v250, v252
	s_nop 0
	v_fmac_f32_e32 v247, v27, v27
	v_fmac_f32_e32 v228, v59, v59
	v_lshlrev_b32_e32 v249, 16, v60
	v_and_b32_e32 v250, s79, v60
	v_lshlrev_b32_e32 v251, 16, v28
	v_and_b32_e32 v252, s79, v28
	v_fma_f32 v28, -s26, v249, v251
	v_fma_f32 v60, -s26, v250, v252
	v_lshlrev_b32_e32 v249, 16, v61
	v_and_b32_e32 v250, s79, v61
	v_lshlrev_b32_e32 v251, 16, v29
	v_and_b32_e32 v252, s79, v29
	v_mul_f32_e32 v248, v28, v28
	v_mul_f32_e32 v229, v60, v60
	v_fma_f32 v29, -s26, v249, v251
	v_fma_f32 v61, -s26, v250, v252
	v_lshlrev_b32_e32 v249, 16, v62
	v_and_b32_e32 v250, s79, v62
	v_lshlrev_b32_e32 v251, 16, v30
	v_and_b32_e32 v252, s79, v30
	v_fmac_f32_e32 v248, v29, v29
	v_fmac_f32_e32 v229, v61, v61
	v_fma_f32 v30, -s26, v249, v251
	v_fma_f32 v62, -s26, v250, v252
	v_lshlrev_b32_e32 v249, 16, v63
	v_and_b32_e32 v250, s79, v63
	v_lshlrev_b32_e32 v251, 16, v31
	v_and_b32_e32 v252, s79, v31
	v_fmac_f32_e32 v248, v30, v30
	v_fmac_f32_e32 v229, v62, v62
	v_fma_f32 v31, -s26, v249, v251
	v_fma_f32 v63, -s26, v250, v252
	s_nop 0
	v_fmac_f32_e32 v248, v31, v31
	v_fmac_f32_e32 v229, v63, v63
	v_add_f32_e32 v241, v241, v222
	v_add_f32_e32 v242, v242, v223
	v_add_f32_e32 v243, v243, v224
	v_add_f32_e32 v244, v244, v225
	v_add_f32_e32 v245, v245, v226
	v_add_f32_e32 v246, v246, v227
	v_add_f32_e32 v247, v247, v228
	v_add_f32_e32 v248, v248, v229
	v_add_f32_dpp v241, v241, v241 quad_perm:[1,0,3,2] row_mask:0xf bank_mask:0xf
; #define GASP __attribute__((address_space(1)))
; __device__ __forceinline__ float lane_xor(float v, int lane, int o) { return __int_as_float(__builtin_amdgcn_ds_bpermute((lane ^ o) << 2, __float_as_int(v))); }
; __device__ __forceinline__ unsigned pk2(float lo, float hi) { return f2bf(lo) | (f2bf(hi) << 16); }
; __device__ __forceinline__ float bflo(unsigned w) { return __uint_as_float(w << 16); }
; __device__ __forceinline__ float bfhi(unsigned w) { return __uint_as_float(w & 0xffff0000u); }
; __global__ void __launch_bounds__(NWAVES * 64, 2) fwd_kernel(Args args) {
;     ...
;                             ss += lane_xor(ss, ln, 1); ss += lane_xor(ss, ln, 2); ss += lane_xor(ss, ln, 4); ss += lane_xor(ss, ln, 8);
;                             const float r = 1.0f / sqrtf(ss * (1.f / 128.f) + 1e-6f);
;                             v4u o;
;                             o[0] = pk2(d[0] * r * sg0[0] * bflo(z[0]), d[1] * r * sg0[1] * bfhi(z[0])); o[1] = pk2(d[2] * r * sg0[2] * bflo(z[1]), d[3] * r * sg0[3] * bfhi(z[1]));
;                             o[2] = pk2(d[4] * r * sg1[0] * bflo(z[2]), d[5] * r * sg1[1] * bfhi(z[2])); o[3] = pk2(d[6] * r * sg1[2] * bflo(z[3]), d[7] * r * sg1[3] * bfhi(z[3]));
;                             *(GASP v4u*)(YCAT + row * 2048 + 1024 + h * 128 + c8) = o; }
	v_add_f32_dpp v242, v242, v242 quad_perm:[1,0,3,2] row_mask:0xf bank_mask:0xf
	v_add_f32_dpp v243, v243, v243 quad_perm:[1,0,3,2] row_mask:0xf bank_mask:0xf
	v_add_f32_dpp v244, v244, v244 quad_perm:[1,0,3,2] row_mask:0xf bank_mask:0xf
	v_add_f32_dpp v245, v245, v245 quad_perm:[1,0,3,2] row_mask:0xf bank_mask:0xf
	v_add_f32_dpp v246, v246, v246 quad_perm:[1,0,3,2] row_mask:0xf bank_mask:0xf
	v_add_f32_dpp v247, v247, v247 quad_perm:[1,0,3,2] row_mask:0xf bank_mask:0xf
	v_add_f32_dpp v248, v248, v248 quad_perm:[1,0,3,2] row_mask:0xf bank_mask:0xf
	v_add_f32_dpp v241, v241, v241 quad_perm:[2,3,0,1] row_mask:0xf bank_mask:0xf
	v_add_f32_dpp v242, v242, v242 quad_perm:[2,3,0,1] row_mask:0xf bank_mask:0xf
	v_add_f32_dpp v243, v243, v243 quad_perm:[2,3,0,1] row_mask:0xf bank_mask:0xf
	v_add_f32_dpp v244, v244, v244 quad_perm:[2,3,0,1] row_mask:0xf bank_mask:0xf
	v_add_f32_dpp v245, v245, v245 quad_perm:[2,3,0,1] row_mask:0xf bank_mask:0xf
	v_add_f32_dpp v246, v246, v246 quad_perm:[2,3,0,1] row_mask:0xf bank_mask:0xf
	v_add_f32_dpp v247, v247, v247 quad_perm:[2,3,0,1] row_mask:0xf bank_mask:0xf
	v_add_f32_dpp v248, v248, v248 quad_perm:[2,3,0,1] row_mask:0xf bank_mask:0xf
	v_add_f32_dpp v241, v241, v241 row_ror:4 row_mask:0xf bank_mask:0xf
	v_add_f32_dpp v242, v242, v242 row_ror:4 row_mask:0xf bank_mask:0xf
	v_add_f32_dpp v243, v243, v243 row_ror:4 row_mask:0xf bank_mask:0xf
	v_add_f32_dpp v244, v244, v244 row_ror:4 row_mask:0xf bank_mask:0xf
	v_add_f32_dpp v245, v245, v245 row_ror:4 row_mask:0xf bank_mask:0xf
	v_add_f32_dpp v246, v246, v246 row_ror:4 row_mask:0xf bank_mask:0xf
	v_add_f32_dpp v247, v247, v247 row_ror:4 row_mask:0xf bank_mask:0xf
	v_add_f32_dpp v248, v248, v248 row_ror:4 row_mask:0xf bank_mask:0xf
	v_add_f32_dpp v241, v241, v241 row_ror:8 row_mask:0xf bank_mask:0xf
	v_add_f32_dpp v242, v242, v242 row_ror:8 row_mask:0xf bank_mask:0xf
	v_add_f32_dpp v243, v243, v243 row_ror:8 row_mask:0xf bank_mask:0xf
	v_add_f32_dpp v244, v244, v244 row_ror:8 row_mask:0xf bank_mask:0xf
	v_add_f32_dpp v245, v245, v245 row_ror:8 row_mask:0xf bank_mask:0xf
	v_add_f32_dpp v246, v246, v246 row_ror:8 row_mask:0xf bank_mask:0xf
	v_add_f32_dpp v247, v247, v247 row_ror:8 row_mask:0xf bank_mask:0xf
	v_add_f32_dpp v248, v248, v248 row_ror:8 row_mask:0xf bank_mask:0xf
	v_fmamk_f32 v241, v241, 0x3c000000, v231
	v_fmamk_f32 v242, v242, 0x3c000000, v231
	v_fmamk_f32 v243, v243, 0x3c000000, v231
	v_fmamk_f32 v244, v244, 0x3c000000, v231
	v_fmamk_f32 v245, v245, 0x3c000000, v231
	v_fmamk_f32 v246, v246, 0x3c000000, v231
	v_fmamk_f32 v247, v247, 0x3c000000, v231
	v_fmamk_f32 v248, v248, 0x3c000000, v231
	v_rsq_f32_e32 v241, v241
	v_rsq_f32_e32 v242, v242
	v_rsq_f32_e32 v243, v243
	v_rsq_f32_e32 v244, v244
	v_rsq_f32_e32 v245, v245
	v_rsq_f32_e32 v246, v246
	v_rsq_f32_e32 v247, v247
	v_rsq_f32_e32 v248, v248
	v_lshlrev_b32_e32 v249, 16, v64
	v_and_b32_e32 v250, s79, v64
	v_mul_f32_e32 v0, v0, v241
	v_mul_f32_e32 v32, v32, v241
	v_mul_f32_e32 v0, v0, v192
	v_mul_f32_e32 v32, v32, v193
	v_mul_f32_e32 v0, v0, v249
	v_mul_f32_e32 v32, v32, v250
	v_cvt_pk_bf16_f32 v64, v0, v32
	v_lshlrev_b32_e32 v251, 16, v65
	v_and_b32_e32 v252, s79, v65
	v_mul_f32_e32 v1, v1, v241
	v_mul_f32_e32 v33, v33, v241
	v_mul_f32_e32 v1, v1, v194
	v_mul_f32_e32 v33, v33, v195
	v_mul_f32_e32 v1, v1, v251
	v_mul_f32_e32 v33, v33, v252
	v_cvt_pk_bf16_f32 v65, v1, v33
	v_lshlrev_b32_e32 v249, 16, v66
	v_and_b32_e32 v250, s79, v66
	v_mul_f32_e32 v2, v2, v241
	v_mul_f32_e32 v34, v34, v241
	v_mul_f32_e32 v2, v2, v196
	v_mul_f32_e32 v34, v34, v197
	v_mul_f32_e32 v2, v2, v249
	v_mul_f32_e32 v34, v34, v250
	v_cvt_pk_bf16_f32 v66, v2, v34
	v_lshlrev_b32_e32 v251, 16, v67
	v_and_b32_e32 v252, s79, v67
	v_mul_f32_e32 v3, v3, v241
	v_mul_f32_e32 v35, v35, v241
	v_mul_f32_e32 v3, v3, v198
	v_mul_f32_e32 v35, v35, v199
	v_mul_f32_e32 v3, v3, v251
	v_mul_f32_e32 v35, v35, v252
	v_cvt_pk_bf16_f32 v67, v3, v35
	global_store_dwordx4 v209, v[64:67], s[28:29]
	v_lshlrev_b32_e32 v249, 16, v68
	v_and_b32_e32 v250, s79, v68
	v_mul_f32_e32 v4, v4, v242
	v_mul_f32_e32 v36, v36, v242
	v_mul_f32_e32 v4, v4, v192
	v_mul_f32_e32 v36, v36, v193
	v_mul_f32_e32 v4, v4, v249
	v_mul_f32_e32 v36, v36, v250
	v_cvt_pk_bf16_f32 v68, v4, v36
	v_lshlrev_b32_e32 v251, 16, v69
	v_and_b32_e32 v252, s79, v69
	v_mul_f32_e32 v5, v5, v242
	v_mul_f32_e32 v37, v37, v242
	v_mul_f32_e32 v5, v5, v194
	v_mul_f32_e32 v37, v37, v195
	v_mul_f32_e32 v5, v5, v251
	v_mul_f32_e32 v37, v37, v252
	v_cvt_pk_bf16_f32 v69, v5, v37
	v_lshlrev_b32_e32 v249, 16, v70
	v_and_b32_e32 v250, s79, v70
	v_mul_f32_e32 v6, v6, v242
	v_mul_f32_e32 v38, v38, v242
	v_mul_f32_e32 v6, v6, v196
	v_mul_f32_e32 v38, v38, v197
	v_mul_f32_e32 v6, v6, v249
	v_mul_f32_e32 v38, v38, v250
	v_cvt_pk_bf16_f32 v70, v6, v38
	v_lshlrev_b32_e32 v251, 16, v71
	v_and_b32_e32 v252, s79, v71
	v_mul_f32_e32 v7, v7, v242
	v_mul_f32_e32 v39, v39, v242
	v_mul_f32_e32 v7, v7, v198
	v_mul_f32_e32 v39, v39, v199
	v_mul_f32_e32 v7, v7, v251
	v_mul_f32_e32 v39, v39, v252
	v_cvt_pk_bf16_f32 v71, v7, v39
	global_store_dwordx4 v210, v[68:71], s[28:29]
	v_lshlrev_b32_e32 v249, 16, v72
	v_and_b32_e32 v250, s79, v72
	v_mul_f32_e32 v8, v8, v243
	v_mul_f32_e32 v40, v40, v243
	v_mul_f32_e32 v8, v8, v192
	v_mul_f32_e32 v40, v40, v193
	v_mul_f32_e32 v8, v8, v249
	v_mul_f32_e32 v40, v40, v250
	v_cvt_pk_bf16_f32 v72, v8, v40
	v_lshlrev_b32_e32 v251, 16, v73
	v_and_b32_e32 v252, s79, v73
	v_mul_f32_e32 v9, v9, v243
	v_mul_f32_e32 v41, v41, v243
	v_mul_f32_e32 v9, v9, v194
	v_mul_f32_e32 v41, v41, v195
	v_mul_f32_e32 v9, v9, v251
	v_mul_f32_e32 v41, v41, v252
	v_cvt_pk_bf16_f32 v73, v9, v41
	v_lshlrev_b32_e32 v249, 16, v74
; #define GASP __attribute__((address_space(1)))
; __device__ __forceinline__ unsigned pk2(float lo, float hi) { return f2bf(lo) | (f2bf(hi) << 16); }
; __device__ __forceinline__ float bflo(unsigned w) { return __uint_as_float(w << 16); }
; __device__ __forceinline__ float bfhi(unsigned w) { return __uint_as_float(w & 0xffff0000u); }
; __global__ void __launch_bounds__(NWAVES * 64, 2) fwd_kernel(Args args) {
;     ...
;                             o[0] = pk2(d[0] * r * sg0[0] * bflo(z[0]), d[1] * r * sg0[1] * bfhi(z[0])); o[1] = pk2(d[2] * r * sg0[2] * bflo(z[1]), d[3] * r * sg0[3] * bfhi(z[1]));
;                             o[2] = pk2(d[4] * r * sg1[0] * bflo(z[2]), d[5] * r * sg1[1] * bfhi(z[2])); o[3] = pk2(d[6] * r * sg1[2] * bflo(z[3]), d[7] * r * sg1[3] * bfhi(z[3]));
;                             *(GASP v4u*)(YCAT + row * 2048 + 1024 + h * 128 + c8) = o; }
	v_and_b32_e32 v250, s79, v74
	v_mul_f32_e32 v10, v10, v243
	v_mul_f32_e32 v42, v42, v243
	v_mul_f32_e32 v10, v10, v196
	v_mul_f32_e32 v42, v42, v197
	v_mul_f32_e32 v10, v10, v249
	v_mul_f32_e32 v42, v42, v250
	v_cvt_pk_bf16_f32 v74, v10, v42
	v_lshlrev_b32_e32 v251, 16, v75
	v_and_b32_e32 v252, s79, v75
	v_mul_f32_e32 v11, v11, v243
	v_mul_f32_e32 v43, v43, v243
	v_mul_f32_e32 v11, v11, v198
	v_mul_f32_e32 v43, v43, v199
	v_mul_f32_e32 v11, v11, v251
	v_mul_f32_e32 v43, v43, v252
	v_cvt_pk_bf16_f32 v75, v11, v43
	global_store_dwordx4 v211, v[72:75], s[28:29]
	v_lshlrev_b32_e32 v249, 16, v76
	v_and_b32_e32 v250, s79, v76
	v_mul_f32_e32 v12, v12, v244
	v_mul_f32_e32 v44, v44, v244
	v_mul_f32_e32 v12, v12, v192
	v_mul_f32_e32 v44, v44, v193
	v_mul_f32_e32 v12, v12, v249
	v_mul_f32_e32 v44, v44, v250
	v_cvt_pk_bf16_f32 v76, v12, v44
	v_lshlrev_b32_e32 v251, 16, v77
	v_and_b32_e32 v252, s79, v77
	v_mul_f32_e32 v13, v13, v244
	v_mul_f32_e32 v45, v45, v244
	v_mul_f32_e32 v13, v13, v194
	v_mul_f32_e32 v45, v45, v195
	v_mul_f32_e32 v13, v13, v251
	v_mul_f32_e32 v45, v45, v252
	v_cvt_pk_bf16_f32 v77, v13, v45
	v_lshlrev_b32_e32 v249, 16, v78
	v_and_b32_e32 v250, s79, v78
	v_mul_f32_e32 v14, v14, v244
	v_mul_f32_e32 v46, v46, v244
	v_mul_f32_e32 v14, v14, v196
	v_mul_f32_e32 v46, v46, v197
	v_mul_f32_e32 v14, v14, v249
	v_mul_f32_e32 v46, v46, v250
	v_cvt_pk_bf16_f32 v78, v14, v46
	v_lshlrev_b32_e32 v251, 16, v79
	v_and_b32_e32 v252, s79, v79
	v_mul_f32_e32 v15, v15, v244
	v_mul_f32_e32 v47, v47, v244
	v_mul_f32_e32 v15, v15, v198
	v_mul_f32_e32 v47, v47, v199
	v_mul_f32_e32 v15, v15, v251
	v_mul_f32_e32 v47, v47, v252
	v_cvt_pk_bf16_f32 v79, v15, v47
	global_store_dwordx4 v214, v[76:79], s[28:29]
	v_lshlrev_b32_e32 v249, 16, v80
	v_and_b32_e32 v250, s79, v80
	v_mul_f32_e32 v16, v16, v245
	v_mul_f32_e32 v48, v48, v245
	v_mul_f32_e32 v16, v16, v192
	v_mul_f32_e32 v48, v48, v193
	v_mul_f32_e32 v16, v16, v249
	v_mul_f32_e32 v48, v48, v250
	v_cvt_pk_bf16_f32 v80, v16, v48
	v_lshlrev_b32_e32 v251, 16, v81
	v_and_b32_e32 v252, s79, v81
	v_mul_f32_e32 v17, v17, v245
	v_mul_f32_e32 v49, v49, v245
	v_mul_f32_e32 v17, v17, v194
	v_mul_f32_e32 v49, v49, v195
	v_mul_f32_e32 v17, v17, v251
	v_mul_f32_e32 v49, v49, v252
	v_cvt_pk_bf16_f32 v81, v17, v49
	v_lshlrev_b32_e32 v249, 16, v82
	v_and_b32_e32 v250, s79, v82
	v_mul_f32_e32 v18, v18, v245
	v_mul_f32_e32 v50, v50, v245
	v_mul_f32_e32 v18, v18, v196
	v_mul_f32_e32 v50, v50, v197
	v_mul_f32_e32 v18, v18, v249
	v_mul_f32_e32 v50, v50, v250
	v_cvt_pk_bf16_f32 v82, v18, v50
	v_lshlrev_b32_e32 v251, 16, v83
	v_and_b32_e32 v252, s79, v83
	v_mul_f32_e32 v19, v19, v245
	v_mul_f32_e32 v51, v51, v245
	v_mul_f32_e32 v19, v19, v198
	v_mul_f32_e32 v51, v51, v199
	v_mul_f32_e32 v19, v19, v251
	v_mul_f32_e32 v51, v51, v252
	v_cvt_pk_bf16_f32 v83, v19, v51
	global_store_dwordx4 v215, v[80:83], s[28:29]
	v_lshlrev_b32_e32 v249, 16, v84
	v_and_b32_e32 v250, s79, v84
	v_mul_f32_e32 v20, v20, v246
	v_mul_f32_e32 v52, v52, v246
	v_mul_f32_e32 v20, v20, v192
	v_mul_f32_e32 v52, v52, v193
	v_mul_f32_e32 v20, v20, v249
	v_mul_f32_e32 v52, v52, v250
	v_cvt_pk_bf16_f32 v84, v20, v52
	v_lshlrev_b32_e32 v251, 16, v85
	v_and_b32_e32 v252, s79, v85
	v_mul_f32_e32 v21, v21, v246
	v_mul_f32_e32 v53, v53, v246
	v_mul_f32_e32 v21, v21, v194
	v_mul_f32_e32 v53, v53, v195
	v_mul_f32_e32 v21, v21, v251
	v_mul_f32_e32 v53, v53, v252
	v_cvt_pk_bf16_f32 v85, v21, v53
	v_lshlrev_b32_e32 v249, 16, v86
	v_and_b32_e32 v250, s79, v86
	v_mul_f32_e32 v22, v22, v246
	v_mul_f32_e32 v54, v54, v246
	v_mul_f32_e32 v22, v22, v196
	v_mul_f32_e32 v54, v54, v197
	v_mul_f32_e32 v22, v22, v249
	v_mul_f32_e32 v54, v54, v250
	v_cvt_pk_bf16_f32 v86, v22, v54
	v_lshlrev_b32_e32 v251, 16, v87
	v_and_b32_e32 v252, s79, v87
	v_mul_f32_e32 v23, v23, v246
	v_mul_f32_e32 v55, v55, v246
	v_mul_f32_e32 v23, v23, v198
	v_mul_f32_e32 v55, v55, v199
	v_mul_f32_e32 v23, v23, v251
	v_mul_f32_e32 v55, v55, v252
	v_cvt_pk_bf16_f32 v87, v23, v55
	global_store_dwordx4 v216, v[84:87], s[28:29]
	v_lshlrev_b32_e32 v249, 16, v88
	v_and_b32_e32 v250, s79, v88
	v_mul_f32_e32 v24, v24, v247
	v_mul_f32_e32 v56, v56, v247
	v_mul_f32_e32 v24, v24, v192
	v_mul_f32_e32 v56, v56, v193
	v_mul_f32_e32 v24, v24, v249
	v_mul_f32_e32 v56, v56, v250
	v_cvt_pk_bf16_f32 v88, v24, v56
	v_lshlrev_b32_e32 v251, 16, v89
	v_and_b32_e32 v252, s79, v89
	v_mul_f32_e32 v25, v25, v247
	v_mul_f32_e32 v57, v57, v247
	v_mul_f32_e32 v25, v25, v194
	v_mul_f32_e32 v57, v57, v195
	v_mul_f32_e32 v25, v25, v251
	v_mul_f32_e32 v57, v57, v252
	v_cvt_pk_bf16_f32 v89, v25, v57
	v_lshlrev_b32_e32 v249, 16, v90
	v_and_b32_e32 v250, s79, v90
	v_mul_f32_e32 v26, v26, v247
	v_mul_f32_e32 v58, v58, v247
	v_mul_f32_e32 v26, v26, v196
	v_mul_f32_e32 v58, v58, v197
	v_mul_f32_e32 v26, v26, v249
	v_mul_f32_e32 v58, v58, v250
	v_cvt_pk_bf16_f32 v90, v26, v58
	v_lshlrev_b32_e32 v251, 16, v91
	v_and_b32_e32 v252, s79, v91
	v_mul_f32_e32 v27, v27, v247
	v_mul_f32_e32 v59, v59, v247
	v_mul_f32_e32 v27, v27, v198
	v_mul_f32_e32 v59, v59, v199
	v_mul_f32_e32 v27, v27, v251
	v_mul_f32_e32 v59, v59, v252
	v_cvt_pk_bf16_f32 v91, v27, v59
	global_store_dwordx4 v217, v[88:91], s[28:29]
	v_lshlrev_b32_e32 v249, 16, v92
	v_and_b32_e32 v250, s79, v92
	v_mul_f32_e32 v28, v28, v248
	v_mul_f32_e32 v60, v60, v248
	v_mul_f32_e32 v28, v28, v192
	v_mul_f32_e32 v60, v60, v193
	v_mul_f32_e32 v28, v28, v249
	v_mul_f32_e32 v60, v60, v250
	v_cvt_pk_bf16_f32 v92, v28, v60
	v_lshlrev_b32_e32 v251, 16, v93
	v_and_b32_e32 v252, s79, v93
	v_mul_f32_e32 v29, v29, v248
	v_mul_f32_e32 v61, v61, v248
	v_mul_f32_e32 v29, v29, v194
	v_mul_f32_e32 v61, v61, v195
	v_mul_f32_e32 v29, v29, v251
	v_mul_f32_e32 v61, v61, v252
	v_cvt_pk_bf16_f32 v93, v29, v61
	v_lshlrev_b32_e32 v249, 16, v94
	v_and_b32_e32 v250, s79, v94
	v_mul_f32_e32 v30, v30, v248
	v_mul_f32_e32 v62, v62, v248
	v_mul_f32_e32 v30, v30, v196
	v_mul_f32_e32 v62, v62, v197
	v_mul_f32_e32 v30, v30, v249
	v_mul_f32_e32 v62, v62, v250
	v_cvt_pk_bf16_f32 v94, v30, v62
	v_lshlrev_b32_e32 v251, 16, v95
	v_and_b32_e32 v252, s79, v95
	v_mul_f32_e32 v31, v31, v248
	v_mul_f32_e32 v63, v63, v248
	v_mul_f32_e32 v31, v31, v198
	v_mul_f32_e32 v63, v63, v199
	v_mul_f32_e32 v31, v31, v251
	v_mul_f32_e32 v63, v63, v252
	v_cvt_pk_bf16_f32 v95, v31, v63
	global_store_dwordx4 v219, v[92:95], s[28:29]
	s_lshl_b32 s21, s75, 24
	s_lshl_b32 s32, s57, 20
	s_add_u32 s21, s21, s32
	s_lshl_b32 s32, s61, 1
	s_add_u32 s21, s21, s32
	s_add_u32 s21, s21, 0x15a00800
	s_add_u32 s28, s8, s21
	s_addc_u32 s29, s9, 0
	s_waitcnt vmcnt(8)
; __device__ __forceinline__ float bflo(unsigned w) { return __uint_as_float(w << 16); }
; __device__ __forceinline__ float bfhi(unsigned w) { return __uint_as_float(w & 0xffff0000u); }
; __global__ void __launch_bounds__(NWAVES * 64, 2) fwd_kernel(Args args) {
;     ...
;                         for (int it = 0; it < 8; ++it) { const size_t row = r0 + it * 4; const v4u p = pp[it], q = qq[it], z = zz[it];
;                             float d[8]; float ss = 0.f;
; #pragma unroll
;                             for (int e = 0; e < 4; ++e) { d[2 * e] = bflo(p[e]) - lam * bflo(q[e]); d[2 * e + 1] = bfhi(p[e]) - lam * bfhi(q[e]); ss += d[2 * e] * d[2 * e] + d[2 * e + 1] * d[2 * e + 1]; }
	v_lshlrev_b32_e32 v249, 16, v128
	v_and_b32_e32 v250, s79, v128
	v_lshlrev_b32_e32 v251, 16, v96
	v_and_b32_e32 v252, s79, v96
	v_fma_f32 v96, -s26, v249, v251
	v_fma_f32 v128, -s26, v250, v252
	v_lshlrev_b32_e32 v249, 16, v129
	v_and_b32_e32 v250, s79, v129
	v_lshlrev_b32_e32 v251, 16, v97
	v_and_b32_e32 v252, s79, v97
	v_mul_f32_e32 v241, v96, v96
	v_mul_f32_e32 v222, v128, v128
	v_fma_f32 v97, -s26, v249, v251
	v_fma_f32 v129, -s26, v250, v252
	v_lshlrev_b32_e32 v249, 16, v130
	v_and_b32_e32 v250, s79, v130
	v_lshlrev_b32_e32 v251, 16, v98
	v_and_b32_e32 v252, s79, v98
	v_fmac_f32_e32 v241, v97, v97
	v_fmac_f32_e32 v222, v129, v129
	v_fma_f32 v98, -s26, v249, v251
	v_fma_f32 v130, -s26, v250, v252
	v_lshlrev_b32_e32 v249, 16, v131
	v_and_b32_e32 v250, s79, v131
	v_lshlrev_b32_e32 v251, 16, v99
	v_and_b32_e32 v252, s79, v99
	v_fmac_f32_e32 v241, v98, v98
	v_fmac_f32_e32 v222, v130, v130
	v_fma_f32 v99, -s26, v249, v251
	v_fma_f32 v131, -s26, v250, v252
	s_nop 0
	v_fmac_f32_e32 v241, v99, v99
	v_fmac_f32_e32 v222, v131, v131
	v_lshlrev_b32_e32 v249, 16, v132
	v_and_b32_e32 v250, s79, v132
	v_lshlrev_b32_e32 v251, 16, v100
	v_and_b32_e32 v252, s79, v100
	v_fma_f32 v100, -s26, v249, v251
	v_fma_f32 v132, -s26, v250, v252
	v_lshlrev_b32_e32 v249, 16, v133
	v_and_b32_e32 v250, s79, v133
	v_lshlrev_b32_e32 v251, 16, v101
	v_and_b32_e32 v252, s79, v101
	v_mul_f32_e32 v242, v100, v100
	v_mul_f32_e32 v223, v132, v132
	v_fma_f32 v101, -s26, v249, v251
	v_fma_f32 v133, -s26, v250, v252
	v_lshlrev_b32_e32 v249, 16, v134
	v_and_b32_e32 v250, s79, v134
	v_lshlrev_b32_e32 v251, 16, v102
	v_and_b32_e32 v252, s79, v102
	v_fmac_f32_e32 v242, v101, v101
	v_fmac_f32_e32 v223, v133, v133
	v_fma_f32 v102, -s26, v249, v251
	v_fma_f32 v134, -s26, v250, v252
	v_lshlrev_b32_e32 v249, 16, v135
	v_and_b32_e32 v250, s79, v135
	v_lshlrev_b32_e32 v251, 16, v103
	v_and_b32_e32 v252, s79, v103
	v_fmac_f32_e32 v242, v102, v102
	v_fmac_f32_e32 v223, v134, v134
	v_fma_f32 v103, -s26, v249, v251
	v_fma_f32 v135, -s26, v250, v252
	s_nop 0
	v_fmac_f32_e32 v242, v103, v103
	v_fmac_f32_e32 v223, v135, v135
	v_lshlrev_b32_e32 v249, 16, v136
	v_and_b32_e32 v250, s79, v136
	v_lshlrev_b32_e32 v251, 16, v104
	v_and_b32_e32 v252, s79, v104
	v_fma_f32 v104, -s26, v249, v251
	v_fma_f32 v136, -s26, v250, v252
	v_lshlrev_b32_e32 v249, 16, v137
	v_and_b32_e32 v250, s79, v137
	v_lshlrev_b32_e32 v251, 16, v105
	v_and_b32_e32 v252, s79, v105
	v_mul_f32_e32 v243, v104, v104
	v_mul_f32_e32 v224, v136, v136
	v_fma_f32 v105, -s26, v249, v251
	v_fma_f32 v137, -s26, v250, v252
	v_lshlrev_b32_e32 v249, 16, v138
	v_and_b32_e32 v250, s79, v138
	v_lshlrev_b32_e32 v251, 16, v106
	v_and_b32_e32 v252, s79, v106
	v_fmac_f32_e32 v243, v105, v105
	v_fmac_f32_e32 v224, v137, v137
	v_fma_f32 v106, -s26, v249, v251
	v_fma_f32 v138, -s26, v250, v252
	v_lshlrev_b32_e32 v249, 16, v139
	v_and_b32_e32 v250, s79, v139
	v_lshlrev_b32_e32 v251, 16, v107
	v_and_b32_e32 v252, s79, v107
	v_fmac_f32_e32 v243, v106, v106
	v_fmac_f32_e32 v224, v138, v138
	v_fma_f32 v107, -s26, v249, v251
	v_fma_f32 v139, -s26, v250, v252
	s_nop 0
	v_fmac_f32_e32 v243, v107, v107
	v_fmac_f32_e32 v224, v139, v139
	v_lshlrev_b32_e32 v249, 16, v140
	v_and_b32_e32 v250, s79, v140
	v_lshlrev_b32_e32 v251, 16, v108
	v_and_b32_e32 v252, s79, v108
	v_fma_f32 v108, -s26, v249, v251
	v_fma_f32 v140, -s26, v250, v252
	v_lshlrev_b32_e32 v249, 16, v141
	v_and_b32_e32 v250, s79, v141
	v_lshlrev_b32_e32 v251, 16, v109
	v_and_b32_e32 v252, s79, v109
	v_mul_f32_e32 v244, v108, v108
	v_mul_f32_e32 v225, v140, v140
	v_fma_f32 v109, -s26, v249, v251
	v_fma_f32 v141, -s26, v250, v252
	v_lshlrev_b32_e32 v249, 16, v142
	v_and_b32_e32 v250, s79, v142
	v_lshlrev_b32_e32 v251, 16, v110
	v_and_b32_e32 v252, s79, v110
	v_fmac_f32_e32 v244, v109, v109
	v_fmac_f32_e32 v225, v141, v141
	v_fma_f32 v110, -s26, v249, v251
	v_fma_f32 v142, -s26, v250, v252
	v_lshlrev_b32_e32 v249, 16, v143
	v_and_b32_e32 v250, s79, v143
	v_lshlrev_b32_e32 v251, 16, v111
	v_and_b32_e32 v252, s79, v111
	v_fmac_f32_e32 v244, v110, v110
	v_fmac_f32_e32 v225, v142, v142
	v_fma_f32 v111, -s26, v249, v251
	v_fma_f32 v143, -s26, v250, v252
	s_nop 0
	v_fmac_f32_e32 v244, v111, v111
	v_fmac_f32_e32 v225, v143, v143
	v_lshlrev_b32_e32 v249, 16, v144
	v_and_b32_e32 v250, s79, v144
	v_lshlrev_b32_e32 v251, 16, v112
	v_and_b32_e32 v252, s79, v112
	v_fma_f32 v112, -s26, v249, v251
	v_fma_f32 v144, -s26, v250, v252
	v_lshlrev_b32_e32 v249, 16, v145
	v_and_b32_e32 v250, s79, v145
	v_lshlrev_b32_e32 v251, 16, v113
	v_and_b32_e32 v252, s79, v113
	v_mul_f32_e32 v245, v112, v112
	v_mul_f32_e32 v226, v144, v144
	v_fma_f32 v113, -s26, v249, v251
	v_fma_f32 v145, -s26, v250, v252
	v_lshlrev_b32_e32 v249, 16, v146
	v_and_b32_e32 v250, s79, v146
	v_lshlrev_b32_e32 v251, 16, v114
	v_and_b32_e32 v252, s79, v114
	v_fmac_f32_e32 v245, v113, v113
	v_fmac_f32_e32 v226, v145, v145
	v_fma_f32 v114, -s26, v249, v251
	v_fma_f32 v146, -s26, v250, v252
	v_lshlrev_b32_e32 v249, 16, v147
	v_and_b32_e32 v250, s79, v147
	v_lshlrev_b32_e32 v251, 16, v115
	v_and_b32_e32 v252, s79, v115
	v_fmac_f32_e32 v245, v114, v114
	v_fmac_f32_e32 v226, v146, v146
	v_fma_f32 v115, -s26, v249, v251
	v_fma_f32 v147, -s26, v250, v252
	s_nop 0
	v_fmac_f32_e32 v245, v115, v115
	v_fmac_f32_e32 v226, v147, v147
	v_lshlrev_b32_e32 v249, 16, v148
	v_and_b32_e32 v250, s79, v148
	v_lshlrev_b32_e32 v251, 16, v116
	v_and_b32_e32 v252, s79, v116
	v_fma_f32 v116, -s26, v249, v251
	v_fma_f32 v148, -s26, v250, v252
	v_lshlrev_b32_e32 v249, 16, v149
	v_and_b32_e32 v250, s79, v149
	v_lshlrev_b32_e32 v251, 16, v117
	v_and_b32_e32 v252, s79, v117
	v_mul_f32_e32 v246, v116, v116
; __device__ __forceinline__ float lane_xor(float v, int lane, int o) { return __int_as_float(__builtin_amdgcn_ds_bpermute((lane ^ o) << 2, __float_as_int(v))); }
; __device__ __forceinline__ float bflo(unsigned w) { return __uint_as_float(w << 16); }
; __device__ __forceinline__ float bfhi(unsigned w) { return __uint_as_float(w & 0xffff0000u); }
; __global__ void __launch_bounds__(NWAVES * 64, 2) fwd_kernel(Args args) {
;     ...
;                         for (int it = 0; it < 8; ++it) { const size_t row = r0 + it * 4; const v4u p = pp[it], q = qq[it], z = zz[it];
;                             float d[8]; float ss = 0.f;
; #pragma unroll
;                             for (int e = 0; e < 4; ++e) { d[2 * e] = bflo(p[e]) - lam * bflo(q[e]); d[2 * e + 1] = bfhi(p[e]) - lam * bfhi(q[e]); ss += d[2 * e] * d[2 * e] + d[2 * e + 1] * d[2 * e + 1]; }
;                             ss += lane_xor(ss, ln, 1); ss += lane_xor(ss, ln, 2); ss += lane_xor(ss, ln, 4); ss += lane_xor(ss, ln, 8);
;                             const float r = 1.0f / sqrtf(ss * (1.f / 128.f) + 1e-6f);
	v_mul_f32_e32 v227, v148, v148
	v_fma_f32 v117, -s26, v249, v251
	v_fma_f32 v149, -s26, v250, v252
	v_lshlrev_b32_e32 v249, 16, v150
	v_and_b32_e32 v250, s79, v150
	v_lshlrev_b32_e32 v251, 16, v118
	v_and_b32_e32 v252, s79, v118
	v_fmac_f32_e32 v246, v117, v117
	v_fmac_f32_e32 v227, v149, v149
	v_fma_f32 v118, -s26, v249, v251
	v_fma_f32 v150, -s26, v250, v252
	v_lshlrev_b32_e32 v249, 16, v151
	v_and_b32_e32 v250, s79, v151
	v_lshlrev_b32_e32 v251, 16, v119
	v_and_b32_e32 v252, s79, v119
	v_fmac_f32_e32 v246, v118, v118
	v_fmac_f32_e32 v227, v150, v150
	v_fma_f32 v119, -s26, v249, v251
	v_fma_f32 v151, -s26, v250, v252
	s_nop 0
	v_fmac_f32_e32 v246, v119, v119
	v_fmac_f32_e32 v227, v151, v151
	v_lshlrev_b32_e32 v249, 16, v152
	v_and_b32_e32 v250, s79, v152
	v_lshlrev_b32_e32 v251, 16, v120
	v_and_b32_e32 v252, s79, v120
	v_fma_f32 v120, -s26, v249, v251
	v_fma_f32 v152, -s26, v250, v252
	v_lshlrev_b32_e32 v249, 16, v153
	v_and_b32_e32 v250, s79, v153
	v_lshlrev_b32_e32 v251, 16, v121
	v_and_b32_e32 v252, s79, v121
	v_mul_f32_e32 v247, v120, v120
	v_mul_f32_e32 v228, v152, v152
	v_fma_f32 v121, -s26, v249, v251
	v_fma_f32 v153, -s26, v250, v252
	v_lshlrev_b32_e32 v249, 16, v154
	v_and_b32_e32 v250, s79, v154
	v_lshlrev_b32_e32 v251, 16, v122
	v_and_b32_e32 v252, s79, v122
	v_fmac_f32_e32 v247, v121, v121
	v_fmac_f32_e32 v228, v153, v153
	v_fma_f32 v122, -s26, v249, v251
	v_fma_f32 v154, -s26, v250, v252
	v_lshlrev_b32_e32 v249, 16, v155
	v_and_b32_e32 v250, s79, v155
	v_lshlrev_b32_e32 v251, 16, v123
	v_and_b32_e32 v252, s79, v123
	v_fmac_f32_e32 v247, v122, v122
	v_fmac_f32_e32 v228, v154, v154
	v_fma_f32 v123, -s26, v249, v251
	v_fma_f32 v155, -s26, v250, v252
	s_nop 0
	v_fmac_f32_e32 v247, v123, v123
	v_fmac_f32_e32 v228, v155, v155
	v_lshlrev_b32_e32 v249, 16, v156
	v_and_b32_e32 v250, s79, v156
	v_lshlrev_b32_e32 v251, 16, v124
	v_and_b32_e32 v252, s79, v124
	v_fma_f32 v124, -s26, v249, v251
	v_fma_f32 v156, -s26, v250, v252
	v_lshlrev_b32_e32 v249, 16, v157
	v_and_b32_e32 v250, s79, v157
	v_lshlrev_b32_e32 v251, 16, v125
	v_and_b32_e32 v252, s79, v125
	v_mul_f32_e32 v248, v124, v124
	v_mul_f32_e32 v229, v156, v156
	v_fma_f32 v125, -s26, v249, v251
	v_fma_f32 v157, -s26, v250, v252
	v_lshlrev_b32_e32 v249, 16, v158
	v_and_b32_e32 v250, s79, v158
	v_lshlrev_b32_e32 v251, 16, v126
	v_and_b32_e32 v252, s79, v126
	v_fmac_f32_e32 v248, v125, v125
	v_fmac_f32_e32 v229, v157, v157
	v_fma_f32 v126, -s26, v249, v251
	v_fma_f32 v158, -s26, v250, v252
	v_lshlrev_b32_e32 v249, 16, v159
	v_and_b32_e32 v250, s79, v159
	v_lshlrev_b32_e32 v251, 16, v127
	v_and_b32_e32 v252, s79, v127
	v_fmac_f32_e32 v248, v126, v126
	v_fmac_f32_e32 v229, v158, v158
	v_fma_f32 v127, -s26, v249, v251
	v_fma_f32 v159, -s26, v250, v252
	s_nop 0
	v_fmac_f32_e32 v248, v127, v127
	v_fmac_f32_e32 v229, v159, v159
	v_add_f32_e32 v241, v241, v222
	v_add_f32_e32 v242, v242, v223
	v_add_f32_e32 v243, v243, v224
	v_add_f32_e32 v244, v244, v225
	v_add_f32_e32 v245, v245, v226
	v_add_f32_e32 v246, v246, v227
	v_add_f32_e32 v247, v247, v228
	v_add_f32_e32 v248, v248, v229
	v_add_f32_dpp v241, v241, v241 quad_perm:[1,0,3,2] row_mask:0xf bank_mask:0xf
	v_add_f32_dpp v242, v242, v242 quad_perm:[1,0,3,2] row_mask:0xf bank_mask:0xf
	v_add_f32_dpp v243, v243, v243 quad_perm:[1,0,3,2] row_mask:0xf bank_mask:0xf
	v_add_f32_dpp v244, v244, v244 quad_perm:[1,0,3,2] row_mask:0xf bank_mask:0xf
	v_add_f32_dpp v245, v245, v245 quad_perm:[1,0,3,2] row_mask:0xf bank_mask:0xf
	v_add_f32_dpp v246, v246, v246 quad_perm:[1,0,3,2] row_mask:0xf bank_mask:0xf
	v_add_f32_dpp v247, v247, v247 quad_perm:[1,0,3,2] row_mask:0xf bank_mask:0xf
	v_add_f32_dpp v248, v248, v248 quad_perm:[1,0,3,2] row_mask:0xf bank_mask:0xf
	v_add_f32_dpp v241, v241, v241 quad_perm:[2,3,0,1] row_mask:0xf bank_mask:0xf
	v_add_f32_dpp v242, v242, v242 quad_perm:[2,3,0,1] row_mask:0xf bank_mask:0xf
	v_add_f32_dpp v243, v243, v243 quad_perm:[2,3,0,1] row_mask:0xf bank_mask:0xf
	v_add_f32_dpp v244, v244, v244 quad_perm:[2,3,0,1] row_mask:0xf bank_mask:0xf
	v_add_f32_dpp v245, v245, v245 quad_perm:[2,3,0,1] row_mask:0xf bank_mask:0xf
	v_add_f32_dpp v246, v246, v246 quad_perm:[2,3,0,1] row_mask:0xf bank_mask:0xf
	v_add_f32_dpp v247, v247, v247 quad_perm:[2,3,0,1] row_mask:0xf bank_mask:0xf
	v_add_f32_dpp v248, v248, v248 quad_perm:[2,3,0,1] row_mask:0xf bank_mask:0xf
	v_add_f32_dpp v241, v241, v241 row_ror:4 row_mask:0xf bank_mask:0xf
	v_add_f32_dpp v242, v242, v242 row_ror:4 row_mask:0xf bank_mask:0xf
	v_add_f32_dpp v243, v243, v243 row_ror:4 row_mask:0xf bank_mask:0xf
	v_add_f32_dpp v244, v244, v244 row_ror:4 row_mask:0xf bank_mask:0xf
	v_add_f32_dpp v245, v245, v245 row_ror:4 row_mask:0xf bank_mask:0xf
	v_add_f32_dpp v246, v246, v246 row_ror:4 row_mask:0xf bank_mask:0xf
	v_add_f32_dpp v247, v247, v247 row_ror:4 row_mask:0xf bank_mask:0xf
	v_add_f32_dpp v248, v248, v248 row_ror:4 row_mask:0xf bank_mask:0xf
	v_add_f32_dpp v241, v241, v241 row_ror:8 row_mask:0xf bank_mask:0xf
	v_add_f32_dpp v242, v242, v242 row_ror:8 row_mask:0xf bank_mask:0xf
	v_add_f32_dpp v243, v243, v243 row_ror:8 row_mask:0xf bank_mask:0xf
	v_add_f32_dpp v244, v244, v244 row_ror:8 row_mask:0xf bank_mask:0xf
	v_add_f32_dpp v245, v245, v245 row_ror:8 row_mask:0xf bank_mask:0xf
	v_add_f32_dpp v246, v246, v246 row_ror:8 row_mask:0xf bank_mask:0xf
	v_add_f32_dpp v247, v247, v247 row_ror:8 row_mask:0xf bank_mask:0xf
	v_add_f32_dpp v248, v248, v248 row_ror:8 row_mask:0xf bank_mask:0xf
	v_fmamk_f32 v241, v241, 0x3c000000, v231
	v_fmamk_f32 v242, v242, 0x3c000000, v231
	v_fmamk_f32 v243, v243, 0x3c000000, v231
	v_fmamk_f32 v244, v244, 0x3c000000, v231
; #define GASP __attribute__((address_space(1)))
; __device__ __forceinline__ unsigned pk2(float lo, float hi) { return f2bf(lo) | (f2bf(hi) << 16); }
; __device__ __forceinline__ float bflo(unsigned w) { return __uint_as_float(w << 16); }
; __device__ __forceinline__ float bfhi(unsigned w) { return __uint_as_float(w & 0xffff0000u); }
; __global__ void __launch_bounds__(NWAVES * 64, 2) fwd_kernel(Args args) {
;     ...
;                             const float r = 1.0f / sqrtf(ss * (1.f / 128.f) + 1e-6f);
;                             v4u o;
;                             o[0] = pk2(d[0] * r * sg0[0] * bflo(z[0]), d[1] * r * sg0[1] * bfhi(z[0])); o[1] = pk2(d[2] * r * sg0[2] * bflo(z[1]), d[3] * r * sg0[3] * bfhi(z[1]));
;                             o[2] = pk2(d[4] * r * sg1[0] * bflo(z[2]), d[5] * r * sg1[1] * bfhi(z[2])); o[3] = pk2(d[6] * r * sg1[2] * bflo(z[3]), d[7] * r * sg1[3] * bfhi(z[3]));
;                             *(GASP v4u*)(YCAT + row * 2048 + 1024 + h * 128 + c8) = o; }
	v_fmamk_f32 v245, v245, 0x3c000000, v231
	v_fmamk_f32 v246, v246, 0x3c000000, v231
	v_fmamk_f32 v247, v247, 0x3c000000, v231
	v_fmamk_f32 v248, v248, 0x3c000000, v231
	v_rsq_f32_e32 v241, v241
	v_rsq_f32_e32 v242, v242
	v_rsq_f32_e32 v243, v243
	v_rsq_f32_e32 v244, v244
	v_rsq_f32_e32 v245, v245
	v_rsq_f32_e32 v246, v246
	v_rsq_f32_e32 v247, v247
	v_rsq_f32_e32 v248, v248
	v_lshlrev_b32_e32 v249, 16, v160
	v_and_b32_e32 v250, s79, v160
	v_mul_f32_e32 v96, v96, v241
	v_mul_f32_e32 v128, v128, v241
	v_mul_f32_e32 v96, v96, v192
	v_mul_f32_e32 v128, v128, v193
	v_mul_f32_e32 v96, v96, v249
	v_mul_f32_e32 v128, v128, v250
	v_cvt_pk_bf16_f32 v160, v96, v128
	v_lshlrev_b32_e32 v251, 16, v161
	v_and_b32_e32 v252, s79, v161
	v_mul_f32_e32 v97, v97, v241
	v_mul_f32_e32 v129, v129, v241
	v_mul_f32_e32 v97, v97, v194
	v_mul_f32_e32 v129, v129, v195
	v_mul_f32_e32 v97, v97, v251
	v_mul_f32_e32 v129, v129, v252
	v_cvt_pk_bf16_f32 v161, v97, v129
	v_lshlrev_b32_e32 v249, 16, v162
	v_and_b32_e32 v250, s79, v162
	v_mul_f32_e32 v98, v98, v241
	v_mul_f32_e32 v130, v130, v241
	v_mul_f32_e32 v98, v98, v196
	v_mul_f32_e32 v130, v130, v197
	v_mul_f32_e32 v98, v98, v249
	v_mul_f32_e32 v130, v130, v250
	v_cvt_pk_bf16_f32 v162, v98, v130
	v_lshlrev_b32_e32 v251, 16, v163
	v_and_b32_e32 v252, s79, v163
	v_mul_f32_e32 v99, v99, v241
	v_mul_f32_e32 v131, v131, v241
	v_mul_f32_e32 v99, v99, v198
	v_mul_f32_e32 v131, v131, v199
	v_mul_f32_e32 v99, v99, v251
	v_mul_f32_e32 v131, v131, v252
	v_cvt_pk_bf16_f32 v163, v99, v131
	global_store_dwordx4 v209, v[160:163], s[28:29]
	v_lshlrev_b32_e32 v249, 16, v164
	v_and_b32_e32 v250, s79, v164
	v_mul_f32_e32 v100, v100, v242
	v_mul_f32_e32 v132, v132, v242
	v_mul_f32_e32 v100, v100, v192
	v_mul_f32_e32 v132, v132, v193
	v_mul_f32_e32 v100, v100, v249
	v_mul_f32_e32 v132, v132, v250
	v_cvt_pk_bf16_f32 v164, v100, v132
	v_lshlrev_b32_e32 v251, 16, v165
	v_and_b32_e32 v252, s79, v165
	v_mul_f32_e32 v101, v101, v242
	v_mul_f32_e32 v133, v133, v242
	v_mul_f32_e32 v101, v101, v194
	v_mul_f32_e32 v133, v133, v195
	v_mul_f32_e32 v101, v101, v251
	v_mul_f32_e32 v133, v133, v252
	v_cvt_pk_bf16_f32 v165, v101, v133
	v_lshlrev_b32_e32 v249, 16, v166
	v_and_b32_e32 v250, s79, v166
	v_mul_f32_e32 v102, v102, v242
	v_mul_f32_e32 v134, v134, v242
	v_mul_f32_e32 v102, v102, v196
	v_mul_f32_e32 v134, v134, v197
	v_mul_f32_e32 v102, v102, v249
	v_mul_f32_e32 v134, v134, v250
	v_cvt_pk_bf16_f32 v166, v102, v134
	v_lshlrev_b32_e32 v251, 16, v167
	v_and_b32_e32 v252, s79, v167
	v_mul_f32_e32 v103, v103, v242
	v_mul_f32_e32 v135, v135, v242
	v_mul_f32_e32 v103, v103, v198
	v_mul_f32_e32 v135, v135, v199
	v_mul_f32_e32 v103, v103, v251
	v_mul_f32_e32 v135, v135, v252
	v_cvt_pk_bf16_f32 v167, v103, v135
	global_store_dwordx4 v210, v[164:167], s[28:29]
	v_lshlrev_b32_e32 v249, 16, v168
	v_and_b32_e32 v250, s79, v168
	v_mul_f32_e32 v104, v104, v243
	v_mul_f32_e32 v136, v136, v243
	v_mul_f32_e32 v104, v104, v192
	v_mul_f32_e32 v136, v136, v193
	v_mul_f32_e32 v104, v104, v249
	v_mul_f32_e32 v136, v136, v250
	v_cvt_pk_bf16_f32 v168, v104, v136
	v_lshlrev_b32_e32 v251, 16, v169
	v_and_b32_e32 v252, s79, v169
	v_mul_f32_e32 v105, v105, v243
	v_mul_f32_e32 v137, v137, v243
	v_mul_f32_e32 v105, v105, v194
	v_mul_f32_e32 v137, v137, v195
	v_mul_f32_e32 v105, v105, v251
	v_mul_f32_e32 v137, v137, v252
	v_cvt_pk_bf16_f32 v169, v105, v137
	v_lshlrev_b32_e32 v249, 16, v170
	v_and_b32_e32 v250, s79, v170
	v_mul_f32_e32 v106, v106, v243
	v_mul_f32_e32 v138, v138, v243
	v_mul_f32_e32 v106, v106, v196
	v_mul_f32_e32 v138, v138, v197
	v_mul_f32_e32 v106, v106, v249
	v_mul_f32_e32 v138, v138, v250
	v_cvt_pk_bf16_f32 v170, v106, v138
	v_lshlrev_b32_e32 v251, 16, v171
	v_and_b32_e32 v252, s79, v171
	v_mul_f32_e32 v107, v107, v243
	v_mul_f32_e32 v139, v139, v243
	v_mul_f32_e32 v107, v107, v198
	v_mul_f32_e32 v139, v139, v199
	v_mul_f32_e32 v107, v107, v251
	v_mul_f32_e32 v139, v139, v252
	v_cvt_pk_bf16_f32 v171, v107, v139
	global_store_dwordx4 v211, v[168:171], s[28:29]
	v_lshlrev_b32_e32 v249, 16, v172
	v_and_b32_e32 v250, s79, v172
	v_mul_f32_e32 v108, v108, v244
	v_mul_f32_e32 v140, v140, v244
	v_mul_f32_e32 v108, v108, v192
	v_mul_f32_e32 v140, v140, v193
	v_mul_f32_e32 v108, v108, v249
	v_mul_f32_e32 v140, v140, v250
	v_cvt_pk_bf16_f32 v172, v108, v140
	v_lshlrev_b32_e32 v251, 16, v173
	v_and_b32_e32 v252, s79, v173
	v_mul_f32_e32 v109, v109, v244
	v_mul_f32_e32 v141, v141, v244
	v_mul_f32_e32 v109, v109, v194
	v_mul_f32_e32 v141, v141, v195
	v_mul_f32_e32 v109, v109, v251
	v_mul_f32_e32 v141, v141, v252
	v_cvt_pk_bf16_f32 v173, v109, v141
	v_lshlrev_b32_e32 v249, 16, v174
	v_and_b32_e32 v250, s79, v174
	v_mul_f32_e32 v110, v110, v244
	v_mul_f32_e32 v142, v142, v244
	v_mul_f32_e32 v110, v110, v196
	v_mul_f32_e32 v142, v142, v197
	v_mul_f32_e32 v110, v110, v249
	v_mul_f32_e32 v142, v142, v250
	v_cvt_pk_bf16_f32 v174, v110, v142
	v_lshlrev_b32_e32 v251, 16, v175
	v_and_b32_e32 v252, s79, v175
	v_mul_f32_e32 v111, v111, v244
	v_mul_f32_e32 v143, v143, v244
	v_mul_f32_e32 v111, v111, v198
	v_mul_f32_e32 v143, v143, v199
; #define GASP __attribute__((address_space(1)))
; __device__ __forceinline__ unsigned pk2(float lo, float hi) { return f2bf(lo) | (f2bf(hi) << 16); }
; __device__ __forceinline__ float bflo(unsigned w) { return __uint_as_float(w << 16); }
; __device__ __forceinline__ float bfhi(unsigned w) { return __uint_as_float(w & 0xffff0000u); }
; __global__ void __launch_bounds__(NWAVES * 64, 2) fwd_kernel(Args args) {
;     ...
;                             o[0] = pk2(d[0] * r * sg0[0] * bflo(z[0]), d[1] * r * sg0[1] * bfhi(z[0])); o[1] = pk2(d[2] * r * sg0[2] * bflo(z[1]), d[3] * r * sg0[3] * bfhi(z[1]));
;                             o[2] = pk2(d[4] * r * sg1[0] * bflo(z[2]), d[5] * r * sg1[1] * bfhi(z[2])); o[3] = pk2(d[6] * r * sg1[2] * bflo(z[3]), d[7] * r * sg1[3] * bfhi(z[3]));
;                             *(GASP v4u*)(YCAT + row * 2048 + 1024 + h * 128 + c8) = o; }
	v_mul_f32_e32 v111, v111, v251
	v_mul_f32_e32 v143, v143, v252
	v_cvt_pk_bf16_f32 v175, v111, v143
	global_store_dwordx4 v214, v[172:175], s[28:29]
	v_lshlrev_b32_e32 v249, 16, v176
	v_and_b32_e32 v250, s79, v176
	v_mul_f32_e32 v112, v112, v245
	v_mul_f32_e32 v144, v144, v245
	v_mul_f32_e32 v112, v112, v192
	v_mul_f32_e32 v144, v144, v193
	v_mul_f32_e32 v112, v112, v249
	v_mul_f32_e32 v144, v144, v250
	v_cvt_pk_bf16_f32 v176, v112, v144
	v_lshlrev_b32_e32 v251, 16, v177
	v_and_b32_e32 v252, s79, v177
	v_mul_f32_e32 v113, v113, v245
	v_mul_f32_e32 v145, v145, v245
	v_mul_f32_e32 v113, v113, v194
	v_mul_f32_e32 v145, v145, v195
	v_mul_f32_e32 v113, v113, v251
	v_mul_f32_e32 v145, v145, v252
	v_cvt_pk_bf16_f32 v177, v113, v145
	v_lshlrev_b32_e32 v249, 16, v178
	v_and_b32_e32 v250, s79, v178
	v_mul_f32_e32 v114, v114, v245
	v_mul_f32_e32 v146, v146, v245
	v_mul_f32_e32 v114, v114, v196
	v_mul_f32_e32 v146, v146, v197
	v_mul_f32_e32 v114, v114, v249
	v_mul_f32_e32 v146, v146, v250
	v_cvt_pk_bf16_f32 v178, v114, v146
	v_lshlrev_b32_e32 v251, 16, v179
	v_and_b32_e32 v252, s79, v179
	v_mul_f32_e32 v115, v115, v245
	v_mul_f32_e32 v147, v147, v245
	v_mul_f32_e32 v115, v115, v198
	v_mul_f32_e32 v147, v147, v199
	v_mul_f32_e32 v115, v115, v251
	v_mul_f32_e32 v147, v147, v252
	v_cvt_pk_bf16_f32 v179, v115, v147
	global_store_dwordx4 v215, v[176:179], s[28:29]
	v_lshlrev_b32_e32 v249, 16, v180
	v_and_b32_e32 v250, s79, v180
	v_mul_f32_e32 v116, v116, v246
	v_mul_f32_e32 v148, v148, v246
	v_mul_f32_e32 v116, v116, v192
	v_mul_f32_e32 v148, v148, v193
	v_mul_f32_e32 v116, v116, v249
	v_mul_f32_e32 v148, v148, v250
	v_cvt_pk_bf16_f32 v180, v116, v148
	v_lshlrev_b32_e32 v251, 16, v181
	v_and_b32_e32 v252, s79, v181
	v_mul_f32_e32 v117, v117, v246
	v_mul_f32_e32 v149, v149, v246
	v_mul_f32_e32 v117, v117, v194
	v_mul_f32_e32 v149, v149, v195
	v_mul_f32_e32 v117, v117, v251
	v_mul_f32_e32 v149, v149, v252
	v_cvt_pk_bf16_f32 v181, v117, v149
	v_lshlrev_b32_e32 v249, 16, v182
	v_and_b32_e32 v250, s79, v182
	v_mul_f32_e32 v118, v118, v246
	v_mul_f32_e32 v150, v150, v246
	v_mul_f32_e32 v118, v118, v196
	v_mul_f32_e32 v150, v150, v197
	v_mul_f32_e32 v118, v118, v249
	v_mul_f32_e32 v150, v150, v250
	v_cvt_pk_bf16_f32 v182, v118, v150
	v_lshlrev_b32_e32 v251, 16, v183
	v_and_b32_e32 v252, s79, v183
	v_mul_f32_e32 v119, v119, v246
	v_mul_f32_e32 v151, v151, v246
	v_mul_f32_e32 v119, v119, v198
	v_mul_f32_e32 v151, v151, v199
	v_mul_f32_e32 v119, v119, v251
	v_mul_f32_e32 v151, v151, v252
	v_cvt_pk_bf16_f32 v183, v119, v151
	global_store_dwordx4 v216, v[180:183], s[28:29]
	v_lshlrev_b32_e32 v249, 16, v184
	v_and_b32_e32 v250, s79, v184
	v_mul_f32_e32 v120, v120, v247
	v_mul_f32_e32 v152, v152, v247
	v_mul_f32_e32 v120, v120, v192
	v_mul_f32_e32 v152, v152, v193
	v_mul_f32_e32 v120, v120, v249
	v_mul_f32_e32 v152, v152, v250
	v_cvt_pk_bf16_f32 v184, v120, v152
	v_lshlrev_b32_e32 v251, 16, v185
	v_and_b32_e32 v252, s79, v185
	v_mul_f32_e32 v121, v121, v247
	v_mul_f32_e32 v153, v153, v247
	v_mul_f32_e32 v121, v121, v194
	v_mul_f32_e32 v153, v153, v195
	v_mul_f32_e32 v121, v121, v251
	v_mul_f32_e32 v153, v153, v252
	v_cvt_pk_bf16_f32 v185, v121, v153
	v_lshlrev_b32_e32 v249, 16, v186
	v_and_b32_e32 v250, s79, v186
	v_mul_f32_e32 v122, v122, v247
	v_mul_f32_e32 v154, v154, v247
	v_mul_f32_e32 v122, v122, v196
	v_mul_f32_e32 v154, v154, v197
	v_mul_f32_e32 v122, v122, v249
	v_mul_f32_e32 v154, v154, v250
	v_cvt_pk_bf16_f32 v186, v122, v154
	v_lshlrev_b32_e32 v251, 16, v187
	v_and_b32_e32 v252, s79, v187
	v_mul_f32_e32 v123, v123, v247
	v_mul_f32_e32 v155, v155, v247
	v_mul_f32_e32 v123, v123, v198
	v_mul_f32_e32 v155, v155, v199
	v_mul_f32_e32 v123, v123, v251
	v_mul_f32_e32 v155, v155, v252
	v_cvt_pk_bf16_f32 v187, v123, v155
	global_store_dwordx4 v217, v[184:187], s[28:29]
	v_lshlrev_b32_e32 v249, 16, v188
	v_and_b32_e32 v250, s79, v188
	v_mul_f32_e32 v124, v124, v248
	v_mul_f32_e32 v156, v156, v248
	v_mul_f32_e32 v124, v124, v192
	v_mul_f32_e32 v156, v156, v193
	v_mul_f32_e32 v124, v124, v249
	v_mul_f32_e32 v156, v156, v250
	v_cvt_pk_bf16_f32 v188, v124, v156
	v_lshlrev_b32_e32 v251, 16, v189
	v_and_b32_e32 v252, s79, v189
	v_mul_f32_e32 v125, v125, v248
	v_mul_f32_e32 v157, v157, v248
	v_mul_f32_e32 v125, v125, v194
	v_mul_f32_e32 v157, v157, v195
	v_mul_f32_e32 v125, v125, v251
	v_mul_f32_e32 v157, v157, v252
	v_cvt_pk_bf16_f32 v189, v125, v157
	v_lshlrev_b32_e32 v249, 16, v190
	v_and_b32_e32 v250, s79, v190
	v_mul_f32_e32 v126, v126, v248
	v_mul_f32_e32 v158, v158, v248
	v_mul_f32_e32 v126, v126, v196
	v_mul_f32_e32 v158, v158, v197
	v_mul_f32_e32 v126, v126, v249
	v_mul_f32_e32 v158, v158, v250
	v_cvt_pk_bf16_f32 v190, v126, v158
	v_lshlrev_b32_e32 v251, 16, v191
	v_and_b32_e32 v252, s79, v191
	v_mul_f32_e32 v127, v127, v248
	v_mul_f32_e32 v159, v159, v248
	v_mul_f32_e32 v127, v127, v198
	v_mul_f32_e32 v159, v159, v199
	v_mul_f32_e32 v127, v127, v251
	v_mul_f32_e32 v159, v159, v252
	v_cvt_pk_bf16_f32 v191, v127, v159
	global_store_dwordx4 v219, v[188:191], s[28:29]
	s_branch .LBB0_398
